# K-loops: remaining chained LDS-DMA addresses in saddr form with per-iteration captured scalar bases (no VALU address math left in w_in/w_out/w_up/w_down loops)
# baseline (speedup 1.0000x reference)
.LBB0_224:
	ds_read_b128 v[144:147], v151
	ds_read_b128 v[154:157], v151 offset:1024
	ds_read_b128 v[158:161], v151 offset:2048
	ds_read_b128 v[162:165], v151 offset:3072
	ds_read_b128 v[166:169], v152
	ds_read_b128 v[170:173], v152 offset:1024
	ds_read_b128 v[174:177], v152 offset:2048
	ds_read_b128 v[178:181], v152 offset:3072
	s_add_u32 s34, s30, 0xfffc0080
	s_addc_u32 s35, s31, -1
	s_cmp_eq_u32 s62, 12
	s_cselect_b32 s37, s15, s35
	s_cselect_b32 s36, s17, s34
	s_cselect_b32 s35, s58, s61
	s_cselect_b32 s34, s59, s60
	s_add_i32 m0, s29, 0xc000
	ds_read_b128 v[182:185], v153
	ds_read_b128 v[186:189], v153 offset:1024
	ds_read_b128 v[190:193], v153 offset:2048
	ds_read_b128 v[194:197], v153 offset:3072
	ds_read_b128 v[198:201], v153 offset:4096
	ds_read_b128 v[202:205], v153 offset:5120
	ds_read_b128 v[206:209], v153 offset:6144
	ds_read_b128 v[210:213], v153 offset:7168
	global_load_lds_dwordx4 v138, s[30:31]
	s_add_i32 m0, s29, 0xe000
	s_nop 0
	global_load_lds_dwordx4 v136, s[30:31]
	s_waitcnt vmcnt(8)
	s_waitcnt lgkmcnt(0)
	s_barrier
	s_setprio 1
	s_waitcnt lgkmcnt(0)
	v_mfma_f32_16x16x32_bf16 v[124:127], v[144:147], v[182:185], v[124:127]
	v_mfma_f32_16x16x32_bf16 v[120:123], v[158:161], v[182:185], v[120:123]
	v_mfma_f32_16x16x32_bf16 v[116:119], v[144:147], v[190:193], v[116:119]
	v_mfma_f32_16x16x32_bf16 v[108:111], v[158:161], v[190:193], v[108:111]
	v_mfma_f32_16x16x32_bf16 v[100:103], v[144:147], v[198:201], v[100:103]
	v_mfma_f32_16x16x32_bf16 v[92:95], v[158:161], v[198:201], v[92:95]
	v_mfma_f32_16x16x32_bf16 v[84:87], v[144:147], v[206:209], v[84:87]
	v_mfma_f32_16x16x32_bf16 v[76:79], v[158:161], v[206:209], v[76:79]
	v_mfma_f32_16x16x32_bf16 v[124:127], v[154:157], v[186:189], v[124:127]
	v_mfma_f32_16x16x32_bf16 v[120:123], v[162:165], v[186:189], v[120:123]
	v_mfma_f32_16x16x32_bf16 v[116:119], v[154:157], v[194:197], v[116:119]
	v_mfma_f32_16x16x32_bf16 v[108:111], v[162:165], v[194:197], v[108:111]
	v_mfma_f32_16x16x32_bf16 v[100:103], v[154:157], v[202:205], v[100:103]
	v_mfma_f32_16x16x32_bf16 v[92:95], v[162:165], v[202:205], v[92:95]
	v_mfma_f32_16x16x32_bf16 v[84:87], v[154:157], v[210:213], v[84:87]
	v_mfma_f32_16x16x32_bf16 v[76:79], v[162:165], v[210:213], v[76:79]
	s_setprio 0
	s_setprio 1
	v_mfma_f32_16x16x32_bf16 v[112:115], v[166:169], v[182:185], v[112:115]
	v_mfma_f32_16x16x32_bf16 v[104:107], v[174:177], v[182:185], v[104:107]
	v_mfma_f32_16x16x32_bf16 v[96:99], v[166:169], v[190:193], v[96:99]
	v_mfma_f32_16x16x32_bf16 v[88:91], v[174:177], v[190:193], v[88:91]
	v_mfma_f32_16x16x32_bf16 v[80:83], v[166:169], v[198:201], v[80:83]
	v_mfma_f32_16x16x32_bf16 v[72:75], v[174:177], v[198:201], v[72:75]
	v_mfma_f32_16x16x32_bf16 v[68:71], v[166:169], v[206:209], v[68:71]
	v_mfma_f32_16x16x32_bf16 v[64:67], v[174:177], v[206:209], v[64:67]
	v_mfma_f32_16x16x32_bf16 v[112:115], v[170:173], v[186:189], v[112:115]
	v_mfma_f32_16x16x32_bf16 v[104:107], v[178:181], v[186:189], v[104:107]
	v_mfma_f32_16x16x32_bf16 v[96:99], v[170:173], v[194:197], v[96:99]
	v_mfma_f32_16x16x32_bf16 v[88:91], v[178:181], v[194:197], v[88:91]
	v_mfma_f32_16x16x32_bf16 v[80:83], v[170:173], v[202:205], v[80:83]
	v_mfma_f32_16x16x32_bf16 v[72:75], v[178:181], v[202:205], v[72:75]
	v_mfma_f32_16x16x32_bf16 v[68:71], v[170:173], v[210:213], v[68:71]
	v_mfma_f32_16x16x32_bf16 v[64:67], v[178:181], v[210:213], v[64:67]
	s_setprio 0
	s_barrier
	s_add_i32 s63, s54, s66
	s_add_u32 s98, s34, s10
	s_addc_u32 s99, s35, s11
	s_add_u32 s100, s36, s10
	s_addc_u32 s101, s37, s11
	s_mov_b32 m0, s63
	ds_read_b128 v[182:185], v153 offset:16384
	ds_read_b128 v[186:189], v153 offset:17408
	ds_read_b128 v[190:193], v153 offset:18432
	ds_read_b128 v[194:197], v153 offset:19456
	ds_read_b128 v[198:201], v153 offset:20480
	ds_read_b128 v[202:205], v153 offset:21504
	ds_read_b128 v[206:209], v153 offset:22528
	ds_read_b128 v[210:213], v153 offset:23552
	global_load_lds_dwordx4 v132, s[34:35]
	s_add_i32 m0, s63, 0x2000
	s_add_u32 s64, s34, 0x40000
	s_addc_u32 s65, s35, 0
	s_add_i32 s63, s55, s66
	global_load_lds_dwordx4 v128, s[34:35]
	s_mov_b32 m0, s63
	s_nop 0
	global_load_lds_dwordx4 v132, s[64:65]
	s_add_i32 m0, s63, 0x2000
	s_nop 0
	global_load_lds_dwordx4 v128, s[64:65]
	s_mov_b32 m0, s29
	s_nop 0
	global_load_lds_dwordx4 v134, s[36:37]
	s_mov_b32 m0, s45
	s_nop 0
	global_load_lds_dwordx4 v130, s[36:37]
	s_waitcnt vmcnt(8)
	s_waitcnt lgkmcnt(0)
	s_barrier
	s_setprio 1
	s_waitcnt lgkmcnt(0)
	v_mfma_f32_16x16x32_bf16 v[60:63], v[144:147], v[182:185], v[60:63]
	v_mfma_f32_16x16x32_bf16 v[56:59], v[158:161], v[182:185], v[56:59]
	v_mfma_f32_16x16x32_bf16 v[52:55], v[144:147], v[190:193], v[52:55]
	v_mfma_f32_16x16x32_bf16 v[44:47], v[158:161], v[190:193], v[44:47]
	v_mfma_f32_16x16x32_bf16 v[36:39], v[144:147], v[198:201], v[36:39]
	v_mfma_f32_16x16x32_bf16 v[28:31], v[158:161], v[198:201], v[28:31]
	v_mfma_f32_16x16x32_bf16 v[20:23], v[144:147], v[206:209], v[20:23]
	v_mfma_f32_16x16x32_bf16 v[12:15], v[158:161], v[206:209], v[12:15]
	v_mfma_f32_16x16x32_bf16 v[60:63], v[154:157], v[186:189], v[60:63]
	v_mfma_f32_16x16x32_bf16 v[56:59], v[162:165], v[186:189], v[56:59]
	v_mfma_f32_16x16x32_bf16 v[52:55], v[154:157], v[194:197], v[52:55]
	v_mfma_f32_16x16x32_bf16 v[44:47], v[162:165], v[194:197], v[44:47]
	v_mfma_f32_16x16x32_bf16 v[36:39], v[154:157], v[202:205], v[36:39]
	v_mfma_f32_16x16x32_bf16 v[28:31], v[162:165], v[202:205], v[28:31]
	v_mfma_f32_16x16x32_bf16 v[20:23], v[154:157], v[210:213], v[20:23]
	v_mfma_f32_16x16x32_bf16 v[12:15], v[162:165], v[210:213], v[12:15]
	s_setprio 0
	s_setprio 1
	v_mfma_f32_16x16x32_bf16 v[48:51], v[166:169], v[182:185], v[48:51]
	v_mfma_f32_16x16x32_bf16 v[40:43], v[174:177], v[182:185], v[40:43]
	v_mfma_f32_16x16x32_bf16 v[32:35], v[166:169], v[190:193], v[32:35]
	v_mfma_f32_16x16x32_bf16 v[24:27], v[174:177], v[190:193], v[24:27]
	v_mfma_f32_16x16x32_bf16 v[16:19], v[166:169], v[198:201], v[16:19]
	v_mfma_f32_16x16x32_bf16 v[8:11], v[174:177], v[198:201], v[8:11]
	v_mfma_f32_16x16x32_bf16 v[4:7], v[166:169], v[206:209], v[4:7]
	v_mfma_f32_16x16x32_bf16 v[0:3], v[174:177], v[206:209], v[0:3]
	v_mfma_f32_16x16x32_bf16 v[48:51], v[170:173], v[186:189], v[48:51]
	v_mfma_f32_16x16x32_bf16 v[40:43], v[178:181], v[186:189], v[40:43]
	v_mfma_f32_16x16x32_bf16 v[32:35], v[170:173], v[194:197], v[32:35]
	v_mfma_f32_16x16x32_bf16 v[24:27], v[178:181], v[194:197], v[24:27]
	v_mfma_f32_16x16x32_bf16 v[16:19], v[170:173], v[202:205], v[16:19]
	v_mfma_f32_16x16x32_bf16 v[8:11], v[178:181], v[202:205], v[8:11]
	v_mfma_f32_16x16x32_bf16 v[4:7], v[170:173], v[210:213], v[4:7]
	v_mfma_f32_16x16x32_bf16 v[0:3], v[178:181], v[210:213], v[0:3]
	s_setprio 0
	s_barrier
	s_add_i32 s63, 0, 0x18000
	s_add_i32 s64, 0, 0x1c000
	v_add_u32_e32 v162, s63, v149
	v_add_u32_e32 v178, s64, v149
	ds_read_b128 v[144:147], v162
	ds_read_b128 v[154:157], v162 offset:1024
	ds_read_b128 v[158:161], v162 offset:2048
	ds_read_b128 v[162:165], v162 offset:3072
	ds_read_b128 v[166:169], v178
	ds_read_b128 v[170:173], v178 offset:1024
	ds_read_b128 v[174:177], v178 offset:2048
	ds_read_b128 v[178:181], v178 offset:3072
	s_add_u32 s36, s36, 0x40000
	s_addc_u32 s37, s37, 0
	s_mov_b32 m0, s46
	ds_read_b128 v[182:185], v153 offset:32768
	ds_read_b128 v[186:189], v153 offset:33792
	ds_read_b128 v[190:193], v153 offset:34816
	ds_read_b128 v[194:197], v153 offset:35840
	ds_read_b128 v[198:201], v153 offset:36864
	ds_read_b128 v[202:205], v153 offset:37888
	ds_read_b128 v[206:209], v153 offset:38912
	ds_read_b128 v[210:213], v153 offset:39936
	global_load_lds_dwordx4 v134, s[36:37]
	s_mov_b32 m0, s47
	s_nop 0
	global_load_lds_dwordx4 v130, s[36:37]
	s_waitcnt vmcnt(8)
	s_waitcnt lgkmcnt(0)
	s_barrier
	s_setprio 1
	s_waitcnt lgkmcnt(0)
	v_mfma_f32_16x16x32_bf16 v[124:127], v[144:147], v[182:185], v[124:127]
	v_mfma_f32_16x16x32_bf16 v[120:123], v[158:161], v[182:185], v[120:123]
	v_mfma_f32_16x16x32_bf16 v[116:119], v[144:147], v[190:193], v[116:119]
	v_mfma_f32_16x16x32_bf16 v[108:111], v[158:161], v[190:193], v[108:111]
	v_mfma_f32_16x16x32_bf16 v[100:103], v[144:147], v[198:201], v[100:103]
	v_mfma_f32_16x16x32_bf16 v[92:95], v[158:161], v[198:201], v[92:95]
	v_mfma_f32_16x16x32_bf16 v[84:87], v[144:147], v[206:209], v[84:87]
	v_mfma_f32_16x16x32_bf16 v[76:79], v[158:161], v[206:209], v[76:79]
	v_mfma_f32_16x16x32_bf16 v[124:127], v[154:157], v[186:189], v[124:127]
	v_mfma_f32_16x16x32_bf16 v[120:123], v[162:165], v[186:189], v[120:123]
	v_mfma_f32_16x16x32_bf16 v[116:119], v[154:157], v[194:197], v[116:119]
	v_mfma_f32_16x16x32_bf16 v[108:111], v[162:165], v[194:197], v[108:111]
	v_mfma_f32_16x16x32_bf16 v[100:103], v[154:157], v[202:205], v[100:103]
	v_mfma_f32_16x16x32_bf16 v[92:95], v[162:165], v[202:205], v[92:95]
	v_mfma_f32_16x16x32_bf16 v[84:87], v[154:157], v[210:213], v[84:87]
	v_mfma_f32_16x16x32_bf16 v[76:79], v[162:165], v[210:213], v[76:79]
	s_setprio 0
	s_setprio 1
	v_mfma_f32_16x16x32_bf16 v[112:115], v[166:169], v[182:185], v[112:115]
	v_mfma_f32_16x16x32_bf16 v[104:107], v[174:177], v[182:185], v[104:107]
	v_mfma_f32_16x16x32_bf16 v[96:99], v[166:169], v[190:193], v[96:99]
	v_mfma_f32_16x16x32_bf16 v[88:91], v[174:177], v[190:193], v[88:91]
	v_mfma_f32_16x16x32_bf16 v[80:83], v[166:169], v[198:201], v[80:83]
	v_mfma_f32_16x16x32_bf16 v[72:75], v[174:177], v[198:201], v[72:75]
	v_mfma_f32_16x16x32_bf16 v[68:71], v[166:169], v[206:209], v[68:71]
	v_mfma_f32_16x16x32_bf16 v[64:67], v[174:177], v[206:209], v[64:67]
	v_mfma_f32_16x16x32_bf16 v[112:115], v[170:173], v[186:189], v[112:115]
	v_mfma_f32_16x16x32_bf16 v[104:107], v[178:181], v[186:189], v[104:107]
	v_mfma_f32_16x16x32_bf16 v[96:99], v[170:173], v[194:197], v[96:99]
	v_mfma_f32_16x16x32_bf16 v[88:91], v[178:181], v[194:197], v[88:91]
	v_mfma_f32_16x16x32_bf16 v[80:83], v[170:173], v[202:205], v[80:83]
	v_mfma_f32_16x16x32_bf16 v[72:75], v[178:181], v[202:205], v[72:75]
	v_mfma_f32_16x16x32_bf16 v[68:71], v[170:173], v[210:213], v[68:71]
	v_mfma_f32_16x16x32_bf16 v[64:67], v[178:181], v[210:213], v[64:67]
	s_setprio 0
	s_barrier
	s_add_i32 s36, s63, s66
	s_mov_b32 m0, s36
	ds_read_b128 v[182:185], v153 offset:49152
	ds_read_b128 v[186:189], v153 offset:50176
	ds_read_b128 v[190:193], v153 offset:51200
	ds_read_b128 v[194:197], v153 offset:52224
	ds_read_b128 v[198:201], v153 offset:53248
	ds_read_b128 v[202:205], v153 offset:54272
	ds_read_b128 v[206:209], v153 offset:55296
	ds_read_b128 v[210:213], v153 offset:56320
	global_load_lds_dwordx4 v132, s[98:99]
	s_add_i32 m0, s36, 0x2000
	s_add_u32 s34, s34, 0x40080
	s_addc_u32 s35, s35, 0
	s_add_i32 s36, s64, s66
	global_load_lds_dwordx4 v128, s[98:99]
	s_mov_b32 m0, s36
	s_nop 0
	global_load_lds_dwordx4 v132, s[34:35]
	s_add_i32 m0, s36, 0x2000
	s_nop 0
	global_load_lds_dwordx4 v128, s[34:35]
	s_mov_b32 m0, s48
	s_nop 0
	global_load_lds_dwordx4 v134, s[100:101]
	s_mov_b32 m0, s49
	s_nop 0
	global_load_lds_dwordx4 v130, s[100:101]
	s_waitcnt vmcnt(8)
	s_waitcnt lgkmcnt(0)
	s_barrier
	s_setprio 1
	s_waitcnt lgkmcnt(0)
	v_mfma_f32_16x16x32_bf16 v[60:63], v[144:147], v[182:185], v[60:63]
	v_mfma_f32_16x16x32_bf16 v[56:59], v[158:161], v[182:185], v[56:59]
	v_mfma_f32_16x16x32_bf16 v[52:55], v[144:147], v[190:193], v[52:55]
	v_mfma_f32_16x16x32_bf16 v[44:47], v[158:161], v[190:193], v[44:47]
	v_mfma_f32_16x16x32_bf16 v[36:39], v[144:147], v[198:201], v[36:39]
	v_mfma_f32_16x16x32_bf16 v[28:31], v[158:161], v[198:201], v[28:31]
	v_mfma_f32_16x16x32_bf16 v[20:23], v[144:147], v[206:209], v[20:23]
	v_mfma_f32_16x16x32_bf16 v[12:15], v[158:161], v[206:209], v[12:15]
	v_mfma_f32_16x16x32_bf16 v[60:63], v[154:157], v[186:189], v[60:63]
	v_mfma_f32_16x16x32_bf16 v[56:59], v[162:165], v[186:189], v[56:59]
	v_mfma_f32_16x16x32_bf16 v[52:55], v[154:157], v[194:197], v[52:55]
	v_mfma_f32_16x16x32_bf16 v[44:47], v[162:165], v[194:197], v[44:47]
	v_mfma_f32_16x16x32_bf16 v[36:39], v[154:157], v[202:205], v[36:39]
	v_mfma_f32_16x16x32_bf16 v[28:31], v[162:165], v[202:205], v[28:31]
	v_mfma_f32_16x16x32_bf16 v[20:23], v[154:157], v[210:213], v[20:23]
	v_mfma_f32_16x16x32_bf16 v[12:15], v[162:165], v[210:213], v[12:15]
	s_setprio 0
	s_setprio 1
	v_mfma_f32_16x16x32_bf16 v[48:51], v[166:169], v[182:185], v[48:51]
	v_mfma_f32_16x16x32_bf16 v[40:43], v[174:177], v[182:185], v[40:43]
	v_mfma_f32_16x16x32_bf16 v[32:35], v[166:169], v[190:193], v[32:35]
	v_mfma_f32_16x16x32_bf16 v[24:27], v[174:177], v[190:193], v[24:27]
	v_mfma_f32_16x16x32_bf16 v[16:19], v[166:169], v[198:201], v[16:19]
	v_mfma_f32_16x16x32_bf16 v[8:11], v[174:177], v[198:201], v[8:11]
	v_mfma_f32_16x16x32_bf16 v[4:7], v[166:169], v[206:209], v[4:7]
	v_mfma_f32_16x16x32_bf16 v[0:3], v[174:177], v[206:209], v[0:3]
	v_mfma_f32_16x16x32_bf16 v[48:51], v[170:173], v[186:189], v[48:51]
	v_mfma_f32_16x16x32_bf16 v[40:43], v[178:181], v[186:189], v[40:43]
	v_mfma_f32_16x16x32_bf16 v[32:35], v[170:173], v[194:197], v[32:35]
	v_mfma_f32_16x16x32_bf16 v[24:27], v[178:181], v[194:197], v[24:27]
	v_mfma_f32_16x16x32_bf16 v[16:19], v[170:173], v[202:205], v[16:19]
	v_mfma_f32_16x16x32_bf16 v[8:11], v[178:181], v[202:205], v[8:11]
	v_mfma_f32_16x16x32_bf16 v[4:7], v[170:173], v[210:213], v[4:7]
	v_mfma_f32_16x16x32_bf16 v[0:3], v[178:181], v[210:213], v[0:3]
	s_setprio 0
	s_barrier
	s_add_i32 s62, s62, 2
	s_add_u32 s60, s60, 0x100
	s_addc_u32 s61, s61, 0
	s_add_u32 s30, s30, 0x100
	s_addc_u32 s31, s31, 0
	s_cmp_gt_u32 s62, 13
	s_cbranch_scc0 .LBB0_224
	s_and_b64 vcc, exec, s[12:13]
	s_cbranch_vccz .LBB0_227
	s_barrier

.LBB0_275:
	s_or_b64 exec, exec, s[2:3]
	s_add_i32 s3, 0, 0x23fa8
	s_mov_b32 s2, -1
	v_mov_b32_e32 v0, s3
	s_barrier
	ds_read_b64 v[0:1], v0
	v_mbcnt_lo_u32_b32 v4, s2, 0
	v_mbcnt_hi_u32_b32 v4, s2, v4
	s_waitcnt lgkmcnt(0)
	v_readfirstlane_b32 s11, v0
	v_readfirstlane_b32 s20, v1
	s_add_u32 s21, s11, 0x4800000
	s_addc_u32 s24, s20, 0
	s_add_i32 s3, 0, 0x23f10
	v_mov_b32_e32 v0, s3
	s_add_i32 s3, 0, 0x23f48
	ds_read_b64 v[6:7], v0
	v_mov_b32_e32 v0, s3
	ds_read2_b64 v[0:3], v0 offset1:1
	s_andn2_b64 vcc, exec, s[0:1]
	s_waitcnt lgkmcnt(1)
	v_readfirstlane_b32 s25, v6
	v_readfirstlane_b32 s26, v7
	s_waitcnt lgkmcnt(0)
	v_readfirstlane_b32 s2, v0
	v_cndmask_b32_e64 v0, 0, 1, s[0:1]
	v_cmp_ne_u32_e64 s[6:7], 1, v0
	v_readfirstlane_b32 s3, v1
	v_mov_b32_e32 v1, 0
	v_readfirstlane_b32 s4, v2
	v_readfirstlane_b32 s5, v3
	v_writelane_b32 v247, s6, 12
	v_lshlrev_b32_e32 v0, 1, v4
	s_nop 0
	v_writelane_b32 v247, s7, 13
	s_cbranch_vccnz .LBB0_278
	s_cmpk_lg_i32 s76, 0x100
	s_cbranch_scc1 .Lnsp_generic
	s_mul_i32 s16, s84, 0x1c00
	s_add_u32 s0, s11, s16
	s_addc_u32 s1, s20, 0
	s_add_u32 s0, s0, 0x4801000
	s_addc_u32 s1, s1, 0
	s_lshl_b32 s16, s84, 7
	s_add_u32 s12, s11, s16
	s_addc_u32 s13, s20, 0
	s_add_u32 s6, s12, 0xb800000
	s_addc_u32 s7, s13, 0
	s_lshl_b32 s16, s84, 2
	s_add_u32 s14, s25, s16
	s_addc_u32 s15, s26, 0
	s_mov_b32 s10, 0x3c800000
	v_and_b32_e32 v9, 7, v4
	v_lshlrev_b32_e32 v5, 4, v4
	v_lshrrev_b32_e32 v13, 3, v4
	v_lshlrev_b32_e32 v7, 18, v13
	v_lshl_add_u32 v7, v9, 4, v7
	v_lshlrev_b32_e32 v14, 13, v13
	global_load_dword v11, v14, s[14:15]
	v_lshlrev_b32_e32 v14, 5, v9
	global_load_dwordx4 v[16:19], v14, s[2:3]
	global_load_dwordx4 v[20:23], v14, s[2:3] offset:16
	v_lshrrev_b32_e32 v8, 4, v4
	v_add_u32_e32 v10, -1, v8
	v_max_i32_e32 v10, 0, v10
	v_lshl_add_u32 v10, v10, 8, v14
	global_load_dwordx4 v[24:27], v10, s[4:5]
	global_load_dwordx4 v[28:31], v10, s[4:5] offset:16
	v_cmp_lt_u32_e64 s[16:17], 47, v4
	v_add_u32_e32 v6, 0x400, v5
	v_add_u32_e32 v14, 0x500, v5
	s_nop 0
	v_cndmask_b32_e64 v6, v6, v14, s[16:17]
	global_load_dwordx4 v[48:51], v5, s[0:1]
	global_load_dwordx4 v[52:55], v6, s[0:1]
	s_add_u32 s0, s0, 0xe00000
	s_addc_u32 s1, s1, 0
	global_load_dwordx4 v[56:59], v5, s[0:1]
	global_load_dwordx4 v[60:63], v6, s[0:1]
	s_add_u32 s0, s0, 0xe00000
	s_addc_u32 s1, s1, 0
	global_load_dwordx4 v[64:67], v5, s[0:1]
	global_load_dwordx4 v[68:71], v6, s[0:1]
	s_add_u32 s0, s0, 0xe00000
	s_addc_u32 s1, s1, 0
	global_load_dwordx4 v[72:75], v5, s[0:1]
	global_load_dwordx4 v[76:79], v6, s[0:1]
	s_add_u32 s0, s0, 0xe00000
	s_addc_u32 s1, s1, 0
	global_load_dwordx4 v[80:83], v5, s[0:1]
	global_load_dwordx4 v[84:87], v6, s[0:1]
	s_add_u32 s0, s0, 0xe00000
	s_addc_u32 s1, s1, 0
	global_load_dwordx4 v[88:91], v5, s[0:1]
	global_load_dwordx4 v[92:95], v6, s[0:1]
	s_add_u32 s0, s0, 0xe00000
	s_addc_u32 s1, s1, 0
	global_load_dwordx4 v[96:99], v5, s[0:1]
	global_load_dwordx4 v[100:103], v6, s[0:1]
	s_add_u32 s0, s0, 0xe00000
	s_addc_u32 s1, s1, 0
	global_load_dwordx4 v[104:107], v5, s[0:1]
	global_load_dwordx4 v[108:111], v6, s[0:1]
	s_add_u32 s0, s0, 0xe00000
	s_addc_u32 s1, s1, 0
	v_cmp_eq_u32_e64 s[16:17], 3, v8
	v_mul_u32_u24_e32 v14, 5, v8
	v_add_u32_e32 v14, 0xc8, v14
	v_cndmask_b32_e64 v10, 0, 5, s[16:17]
	v_add_u32_e32 v14, v14, v10
	v_lshlrev_b32_e32 v14, 20, v14
	v_and_b32_e32 v13, 1, v13
	v_lshl_add_u32 v14, v13, 18, v14
	v_cmp_eq_u32_e64 s[18:19], 1, v8
	v_lshl_add_u32 v8, v9, 4, v14
	v_cmp_eq_u32_e64 s[16:17], 0, v9
	v_mov_b32_e32 v10, 0
	v_mov_b32_e32 v15, 0x358637bd
	v_cndmask_b32_e64 v10, v10, -1.0, s[16:17]
	v_cmp_eq_u32_e64 s[16:17], 1, v9
	s_nop 1
	v_cndmask_b32_e64 v10, v10, 1.0, s[16:17]
	v_mov_b32_e32 v13, 1.0
	v_cmp_eq_u32_e32 vcc, 1, v9
	v_mov_b32_e32 v14, 0x3e4693af
	s_nop 0
	v_cndmask_b32_e32 v13, v13, v14, vcc
	v_cmp_eq_u32_e32 vcc, 2, v9
	v_mov_b32_e32 v14, 0x3d1a08c8
	s_nop 0
	v_cndmask_b32_e32 v13, v13, v14, vcc
	v_cmp_eq_u32_e32 vcc, 3, v9
	v_mov_b32_e32 v14, 0x3beef74e
	s_nop 0
	v_cndmask_b32_e32 v13, v13, v14, vcc
	v_cmp_eq_u32_e32 vcc, 4, v9
	v_mov_b32_e32 v14, 0x3ab95d22
	s_nop 0
	v_cndmask_b32_e32 v13, v13, v14, vcc
	v_cmp_eq_u32_e32 vcc, 5, v9
	v_mov_b32_e32 v14, 0x398fc8f8
	s_nop 0
	v_cndmask_b32_e32 v13, v13, v14, vcc
	v_cmp_eq_u32_e32 vcc, 6, v9
	v_mov_b32_e32 v14, 0x385f10c4
	s_nop 0
	v_cndmask_b32_e32 v13, v13, v14, vcc
	v_cmp_eq_u32_e32 vcc, 7, v9
	v_mov_b32_e32 v14, 0x372d07a7
	s_nop 0
	v_cndmask_b32_e32 v13, v13, v14, vcc
	s_waitcnt vmcnt(20)
	v_cvt_f32_i32_e32 v11, v11
	v_mul_f32_e32 v11, v13, v11
	v_mul_f32_e32 v14, 0.15915494, v11
	v_floor_f32_e32 v14, v14
	v_fma_f32 v14, v11, 0.15915494, -v14
	v_cos_f32_e32 v11, v14
	v_sin_f32_e32 v12, v14
	v_cmp_gt_u32_e32 vcc, 2, v9
	s_waitcnt vmcnt(16)
	s_waitcnt vmcnt(14)
	v_readlane_b32 s28, v11, 0
	v_readlane_b32 s38, v12, 0
	v_readlane_b32 s29, v11, 1
	v_readlane_b32 s39, v12, 1
	v_readlane_b32 s30, v11, 2
	v_readlane_b32 s40, v12, 2
	v_readlane_b32 s31, v11, 3
	v_readlane_b32 s41, v12, 3
	v_readlane_b32 s34, v11, 4
	v_readlane_b32 s42, v12, 4
	v_readlane_b32 s35, v11, 5
	v_readlane_b32 s43, v12, 5
	v_readlane_b32 s36, v11, 6
	v_readlane_b32 s44, v12, 6
	v_readlane_b32 s37, v11, 7
	v_readlane_b32 s45, v12, 7
	v_mul_f32_e32 v32, s38, v10
	v_mul_f32_e32 v33, s39, v10
	v_mul_f32_e32 v34, s40, v10
	v_mul_f32_e32 v35, s41, v10
	v_mul_f32_e32 v36, s42, v10
	v_mul_f32_e32 v37, s43, v10
	v_mul_f32_e32 v38, s44, v10
	v_mul_f32_e32 v39, s45, v10
	v_lshlrev_b32_e32 v112, 16, v48
	v_and_b32_e32 v113, 0xffff0000, v48
	v_lshlrev_b32_e32 v114, 16, v49
	v_and_b32_e32 v115, 0xffff0000, v49
	v_lshlrev_b32_e32 v116, 16, v50
	v_and_b32_e32 v117, 0xffff0000, v50
	v_lshlrev_b32_e32 v118, 16, v51
	v_and_b32_e32 v119, 0xffff0000, v51
	v_mul_f32_e32 v140, v112, v112
	v_mul_f32_e32 v141, v113, v113
	v_fmac_f32_e32 v140, v114, v114
	v_fmac_f32_e32 v141, v115, v115
	v_fmac_f32_e32 v140, v116, v116
	v_fmac_f32_e32 v141, v117, v117
	v_fmac_f32_e32 v140, v118, v118
	v_fmac_f32_e32 v141, v119, v119
	v_add_f32_e32 v140, v140, v141
	s_nop 1
	v_add_f32_dpp v140, v140, v140 quad_perm:[1,0,3,2] row_mask:0xf bank_mask:0xf bound_ctrl:1
	s_nop 1
	v_add_f32_dpp v140, v140, v140 quad_perm:[2,3,0,1] row_mask:0xf bank_mask:0xf bound_ctrl:1
	s_nop 1
	v_add_f32_dpp v140, v140, v140 row_half_mirror row_mask:0xf bank_mask:0xf bound_ctrl:1
	v_fma_f32 v141, v140, s10, v15
	v_rsq_f32_e32 v141, v141
	s_nop 0
	v_mul_f32_e32 v112, v112, v141
	v_mul_f32_e32 v113, v113, v141
	v_mul_f32_e32 v114, v114, v141
	v_mul_f32_e32 v115, v115, v141
	v_mul_f32_e32 v116, v116, v141
	v_mul_f32_e32 v117, v117, v141
	v_mul_f32_e32 v118, v118, v141
	v_mul_f32_e32 v119, v119, v141
	v_mul_f32_e32 v112, v112, v16
	v_mul_f32_e32 v113, v113, v17
	v_mul_f32_e32 v114, v114, v18
	v_mul_f32_e32 v115, v115, v19
	v_mul_f32_e32 v116, v116, v20
	v_mul_f32_e32 v117, v117, v21
	v_mul_f32_e32 v118, v118, v22
	v_mul_f32_e32 v119, v119, v23
	v_mov_b32_dpp v120, v112 quad_perm:[1,0,3,2] row_mask:0xf bank_mask:0xf
	v_mov_b32_dpp v121, v113 quad_perm:[1,0,3,2] row_mask:0xf bank_mask:0xf
	v_mov_b32_dpp v122, v114 quad_perm:[1,0,3,2] row_mask:0xf bank_mask:0xf
	v_mov_b32_dpp v123, v115 quad_perm:[1,0,3,2] row_mask:0xf bank_mask:0xf
	v_mov_b32_dpp v124, v116 quad_perm:[1,0,3,2] row_mask:0xf bank_mask:0xf
	v_mov_b32_dpp v125, v117 quad_perm:[1,0,3,2] row_mask:0xf bank_mask:0xf
	v_mov_b32_dpp v126, v118 quad_perm:[1,0,3,2] row_mask:0xf bank_mask:0xf
	v_mov_b32_dpp v127, v119 quad_perm:[1,0,3,2] row_mask:0xf bank_mask:0xf
	v_mul_f32_e32 v128, s28, v112
	v_mul_f32_e32 v129, s29, v113
	v_mul_f32_e32 v130, s30, v114
	v_mul_f32_e32 v131, s31, v115
	v_mul_f32_e32 v132, s34, v116
	v_mul_f32_e32 v133, s35, v117
	v_mul_f32_e32 v134, s36, v118
	v_mul_f32_e32 v135, s37, v119
	v_fmac_f32_e32 v128, v32, v120
	v_fmac_f32_e32 v129, v33, v121
	v_fmac_f32_e32 v130, v34, v122
	v_fmac_f32_e32 v131, v35, v123
	v_fmac_f32_e32 v132, v36, v124
	v_fmac_f32_e32 v133, v37, v125
	v_fmac_f32_e32 v134, v38, v126
	v_fmac_f32_e32 v135, v39, v127
	v_cndmask_b32_e32 v112, v112, v128, vcc
	v_cndmask_b32_e32 v113, v113, v129, vcc
	v_cndmask_b32_e32 v114, v114, v130, vcc
	v_cndmask_b32_e32 v115, v115, v131, vcc
	v_cndmask_b32_e32 v116, v116, v132, vcc
	v_cndmask_b32_e32 v117, v117, v133, vcc
	v_cndmask_b32_e32 v118, v118, v134, vcc
	v_cndmask_b32_e32 v119, v119, v135, vcc
	v_mul_f32_e32 v112, 0x3e38aa3b, v112
	v_mul_f32_e32 v113, 0x3e38aa3b, v113
	v_mul_f32_e32 v114, 0x3e38aa3b, v114
	v_mul_f32_e32 v115, 0x3e38aa3b, v115
	v_mul_f32_e32 v116, 0x3e38aa3b, v116
	v_mul_f32_e32 v117, 0x3e38aa3b, v117
	v_mul_f32_e32 v118, 0x3e38aa3b, v118
	v_mul_f32_e32 v119, 0x3e38aa3b, v119
	v_cvt_pk_bf16_f32 v136, v112, v113
	v_cvt_pk_bf16_f32 v137, v114, v115
	v_cvt_pk_bf16_f32 v138, v116, v117
	v_cvt_pk_bf16_f32 v139, v118, v119
	global_store_dwordx4 v7, v[136:139], s[6:7]
	s_nop 1
	v_lshlrev_b32_e32 v112, 16, v52
	v_and_b32_e32 v113, 0xffff0000, v52
	v_lshlrev_b32_e32 v114, 16, v53
	v_and_b32_e32 v115, 0xffff0000, v53
	v_lshlrev_b32_e32 v116, 16, v54
	v_and_b32_e32 v117, 0xffff0000, v54
	v_lshlrev_b32_e32 v118, 16, v55
	v_and_b32_e32 v119, 0xffff0000, v55
	v_mul_f32_e32 v140, v112, v112
	v_mul_f32_e32 v141, v113, v113
	v_fmac_f32_e32 v140, v114, v114
	v_fmac_f32_e32 v141, v115, v115
	v_fmac_f32_e32 v140, v116, v116
	v_fmac_f32_e32 v141, v117, v117
	v_fmac_f32_e32 v140, v118, v118
	v_fmac_f32_e32 v141, v119, v119
	v_add_f32_e32 v140, v140, v141
	s_nop 1
	v_add_f32_dpp v140, v140, v140 quad_perm:[1,0,3,2] row_mask:0xf bank_mask:0xf bound_ctrl:1
	s_nop 1
	v_add_f32_dpp v140, v140, v140 quad_perm:[2,3,0,1] row_mask:0xf bank_mask:0xf bound_ctrl:1
	s_nop 1
	v_add_f32_dpp v140, v140, v140 row_half_mirror row_mask:0xf bank_mask:0xf bound_ctrl:1
	v_fma_f32 v141, v140, s10, v15
	v_rsq_f32_e32 v141, v141
	s_nop 0
	v_mul_f32_e32 v112, v112, v141
	v_mul_f32_e32 v113, v113, v141
	v_mul_f32_e32 v114, v114, v141
	v_mul_f32_e32 v115, v115, v141
	v_mul_f32_e32 v116, v116, v141
	v_mul_f32_e32 v117, v117, v141
	v_mul_f32_e32 v118, v118, v141
	v_mul_f32_e32 v119, v119, v141
	v_mul_f32_e32 v112, v112, v24
	v_mul_f32_e32 v113, v113, v25
	v_mul_f32_e32 v114, v114, v26
	v_mul_f32_e32 v115, v115, v27
	v_mul_f32_e32 v116, v116, v28
	v_mul_f32_e32 v117, v117, v29
	v_mul_f32_e32 v118, v118, v30
	v_mul_f32_e32 v119, v119, v31
	v_mov_b32_dpp v120, v112 quad_perm:[1,0,3,2] row_mask:0xf bank_mask:0xf
	v_mov_b32_dpp v121, v113 quad_perm:[1,0,3,2] row_mask:0xf bank_mask:0xf
	v_mov_b32_dpp v122, v114 quad_perm:[1,0,3,2] row_mask:0xf bank_mask:0xf
	v_mov_b32_dpp v123, v115 quad_perm:[1,0,3,2] row_mask:0xf bank_mask:0xf
	v_mov_b32_dpp v124, v116 quad_perm:[1,0,3,2] row_mask:0xf bank_mask:0xf
	v_mov_b32_dpp v125, v117 quad_perm:[1,0,3,2] row_mask:0xf bank_mask:0xf
	v_mov_b32_dpp v126, v118 quad_perm:[1,0,3,2] row_mask:0xf bank_mask:0xf
	v_mov_b32_dpp v127, v119 quad_perm:[1,0,3,2] row_mask:0xf bank_mask:0xf
	v_mul_f32_e32 v128, s28, v112
	v_mul_f32_e32 v129, s29, v113
	v_mul_f32_e32 v130, s30, v114
	v_mul_f32_e32 v131, s31, v115
	v_mul_f32_e32 v132, s34, v116
	v_mul_f32_e32 v133, s35, v117
	v_mul_f32_e32 v134, s36, v118
	v_mul_f32_e32 v135, s37, v119
	v_fmac_f32_e32 v128, v32, v120
	v_fmac_f32_e32 v129, v33, v121
	v_fmac_f32_e32 v130, v34, v122
	v_fmac_f32_e32 v131, v35, v123
	v_fmac_f32_e32 v132, v36, v124
	v_fmac_f32_e32 v133, v37, v125
	v_fmac_f32_e32 v134, v38, v126
	v_fmac_f32_e32 v135, v39, v127
	v_cndmask_b32_e32 v112, v112, v128, vcc
	v_cndmask_b32_e32 v113, v113, v129, vcc
	v_cndmask_b32_e32 v114, v114, v130, vcc
	v_cndmask_b32_e32 v115, v115, v131, vcc
	v_cndmask_b32_e32 v116, v116, v132, vcc
	v_cndmask_b32_e32 v117, v117, v133, vcc
	v_cndmask_b32_e32 v118, v118, v134, vcc
	v_cndmask_b32_e32 v119, v119, v135, vcc
	v_cvt_pk_bf16_f32 v136, v112, v113
	v_cvt_pk_bf16_f32 v137, v114, v115
	v_cvt_pk_bf16_f32 v138, v116, v117
	v_cvt_pk_bf16_f32 v139, v118, v119
	v_cndmask_b32_e64 v136, v136, v52, s[18:19]
	v_cndmask_b32_e64 v137, v137, v53, s[18:19]
	v_cndmask_b32_e64 v138, v138, v54, s[18:19]
	v_cndmask_b32_e64 v139, v139, v55, s[18:19]
	global_store_dwordx4 v8, v[136:139], s[12:13]
	s_add_u32 s6, s6, 0x200000
	s_addc_u32 s7, s7, 0
	s_add_u32 s12, s12, 0x80000
	s_addc_u32 s13, s13, 0
	s_waitcnt vmcnt(14)
	v_readlane_b32 s28, v11, 8
	v_readlane_b32 s38, v12, 8
	v_readlane_b32 s29, v11, 9
	v_readlane_b32 s39, v12, 9
	v_readlane_b32 s30, v11, 10
	v_readlane_b32 s40, v12, 10
	v_readlane_b32 s31, v11, 11
	v_readlane_b32 s41, v12, 11
	v_readlane_b32 s34, v11, 12
	v_readlane_b32 s42, v12, 12
	v_readlane_b32 s35, v11, 13
	v_readlane_b32 s43, v12, 13
	v_readlane_b32 s36, v11, 14
	v_readlane_b32 s44, v12, 14
	v_readlane_b32 s37, v11, 15
	v_readlane_b32 s45, v12, 15
	v_mul_f32_e32 v32, s38, v10
	v_mul_f32_e32 v33, s39, v10
	v_mul_f32_e32 v34, s40, v10
	v_mul_f32_e32 v35, s41, v10
	v_mul_f32_e32 v36, s42, v10
	v_mul_f32_e32 v37, s43, v10
	v_mul_f32_e32 v38, s44, v10
	v_mul_f32_e32 v39, s45, v10
	v_lshlrev_b32_e32 v112, 16, v56
	v_and_b32_e32 v113, 0xffff0000, v56
	v_lshlrev_b32_e32 v114, 16, v57
	v_and_b32_e32 v115, 0xffff0000, v57
	v_lshlrev_b32_e32 v116, 16, v58
	v_and_b32_e32 v117, 0xffff0000, v58
	v_lshlrev_b32_e32 v118, 16, v59
	v_and_b32_e32 v119, 0xffff0000, v59
	v_mul_f32_e32 v140, v112, v112
	v_mul_f32_e32 v141, v113, v113
	v_fmac_f32_e32 v140, v114, v114
	v_fmac_f32_e32 v141, v115, v115
	v_fmac_f32_e32 v140, v116, v116
	v_fmac_f32_e32 v141, v117, v117
	v_fmac_f32_e32 v140, v118, v118
	v_fmac_f32_e32 v141, v119, v119
	v_add_f32_e32 v140, v140, v141
	s_nop 1
	v_add_f32_dpp v140, v140, v140 quad_perm:[1,0,3,2] row_mask:0xf bank_mask:0xf bound_ctrl:1
	s_nop 1
	v_add_f32_dpp v140, v140, v140 quad_perm:[2,3,0,1] row_mask:0xf bank_mask:0xf bound_ctrl:1
	s_nop 1
	v_add_f32_dpp v140, v140, v140 row_half_mirror row_mask:0xf bank_mask:0xf bound_ctrl:1
	v_fma_f32 v141, v140, s10, v15
	v_rsq_f32_e32 v141, v141
	s_nop 0
	v_mul_f32_e32 v112, v112, v141
	v_mul_f32_e32 v113, v113, v141
	v_mul_f32_e32 v114, v114, v141
	v_mul_f32_e32 v115, v115, v141
	v_mul_f32_e32 v116, v116, v141
	v_mul_f32_e32 v117, v117, v141
	v_mul_f32_e32 v118, v118, v141
	v_mul_f32_e32 v119, v119, v141
	v_mul_f32_e32 v112, v112, v16
	v_mul_f32_e32 v113, v113, v17
	v_mul_f32_e32 v114, v114, v18
	v_mul_f32_e32 v115, v115, v19
	v_mul_f32_e32 v116, v116, v20
	v_mul_f32_e32 v117, v117, v21
	v_mul_f32_e32 v118, v118, v22
	v_mul_f32_e32 v119, v119, v23
	v_mov_b32_dpp v120, v112 quad_perm:[1,0,3,2] row_mask:0xf bank_mask:0xf
	v_mov_b32_dpp v121, v113 quad_perm:[1,0,3,2] row_mask:0xf bank_mask:0xf
	v_mov_b32_dpp v122, v114 quad_perm:[1,0,3,2] row_mask:0xf bank_mask:0xf
	v_mov_b32_dpp v123, v115 quad_perm:[1,0,3,2] row_mask:0xf bank_mask:0xf
	v_mov_b32_dpp v124, v116 quad_perm:[1,0,3,2] row_mask:0xf bank_mask:0xf
	v_mov_b32_dpp v125, v117 quad_perm:[1,0,3,2] row_mask:0xf bank_mask:0xf
	v_mov_b32_dpp v126, v118 quad_perm:[1,0,3,2] row_mask:0xf bank_mask:0xf
	v_mov_b32_dpp v127, v119 quad_perm:[1,0,3,2] row_mask:0xf bank_mask:0xf
	v_mul_f32_e32 v128, s28, v112
	v_mul_f32_e32 v129, s29, v113
	v_mul_f32_e32 v130, s30, v114
	v_mul_f32_e32 v131, s31, v115
	v_mul_f32_e32 v132, s34, v116
	v_mul_f32_e32 v133, s35, v117
	v_mul_f32_e32 v134, s36, v118
	v_mul_f32_e32 v135, s37, v119
	v_fmac_f32_e32 v128, v32, v120
	v_fmac_f32_e32 v129, v33, v121
	v_fmac_f32_e32 v130, v34, v122
	v_fmac_f32_e32 v131, v35, v123
	v_fmac_f32_e32 v132, v36, v124
	v_fmac_f32_e32 v133, v37, v125
	v_fmac_f32_e32 v134, v38, v126
	v_fmac_f32_e32 v135, v39, v127
	v_cndmask_b32_e32 v112, v112, v128, vcc
	v_cndmask_b32_e32 v113, v113, v129, vcc
	v_cndmask_b32_e32 v114, v114, v130, vcc
	v_cndmask_b32_e32 v115, v115, v131, vcc
	v_cndmask_b32_e32 v116, v116, v132, vcc
	v_cndmask_b32_e32 v117, v117, v133, vcc
	v_cndmask_b32_e32 v118, v118, v134, vcc
	v_cndmask_b32_e32 v119, v119, v135, vcc
	v_mul_f32_e32 v112, 0x3e38aa3b, v112
	v_mul_f32_e32 v113, 0x3e38aa3b, v113
	v_mul_f32_e32 v114, 0x3e38aa3b, v114
	v_mul_f32_e32 v115, 0x3e38aa3b, v115
	v_mul_f32_e32 v116, 0x3e38aa3b, v116
	v_mul_f32_e32 v117, 0x3e38aa3b, v117
	v_mul_f32_e32 v118, 0x3e38aa3b, v118
	v_mul_f32_e32 v119, 0x3e38aa3b, v119
	v_cvt_pk_bf16_f32 v136, v112, v113
	v_cvt_pk_bf16_f32 v137, v114, v115
	v_cvt_pk_bf16_f32 v138, v116, v117
	v_cvt_pk_bf16_f32 v139, v118, v119
	global_store_dwordx4 v7, v[136:139], s[6:7]
	s_nop 1
	v_lshlrev_b32_e32 v112, 16, v60
	v_and_b32_e32 v113, 0xffff0000, v60
	v_lshlrev_b32_e32 v114, 16, v61
	v_and_b32_e32 v115, 0xffff0000, v61
	v_lshlrev_b32_e32 v116, 16, v62
	v_and_b32_e32 v117, 0xffff0000, v62
	v_lshlrev_b32_e32 v118, 16, v63
	v_and_b32_e32 v119, 0xffff0000, v63
	v_mul_f32_e32 v140, v112, v112
	v_mul_f32_e32 v141, v113, v113
	v_fmac_f32_e32 v140, v114, v114
	v_fmac_f32_e32 v141, v115, v115
	v_fmac_f32_e32 v140, v116, v116
	v_fmac_f32_e32 v141, v117, v117
	v_fmac_f32_e32 v140, v118, v118
	v_fmac_f32_e32 v141, v119, v119
	v_add_f32_e32 v140, v140, v141
	s_nop 1
	v_add_f32_dpp v140, v140, v140 quad_perm:[1,0,3,2] row_mask:0xf bank_mask:0xf bound_ctrl:1
	s_nop 1
	v_add_f32_dpp v140, v140, v140 quad_perm:[2,3,0,1] row_mask:0xf bank_mask:0xf bound_ctrl:1
	s_nop 1
	v_add_f32_dpp v140, v140, v140 row_half_mirror row_mask:0xf bank_mask:0xf bound_ctrl:1
	v_fma_f32 v141, v140, s10, v15
	v_rsq_f32_e32 v141, v141
	s_nop 0
	v_mul_f32_e32 v112, v112, v141
	v_mul_f32_e32 v113, v113, v141
	v_mul_f32_e32 v114, v114, v141
	v_mul_f32_e32 v115, v115, v141
	v_mul_f32_e32 v116, v116, v141
	v_mul_f32_e32 v117, v117, v141
	v_mul_f32_e32 v118, v118, v141
	v_mul_f32_e32 v119, v119, v141
	v_mul_f32_e32 v112, v112, v24
	v_mul_f32_e32 v113, v113, v25
	v_mul_f32_e32 v114, v114, v26
	v_mul_f32_e32 v115, v115, v27
	v_mul_f32_e32 v116, v116, v28
	v_mul_f32_e32 v117, v117, v29
	v_mul_f32_e32 v118, v118, v30
	v_mul_f32_e32 v119, v119, v31
	v_mov_b32_dpp v120, v112 quad_perm:[1,0,3,2] row_mask:0xf bank_mask:0xf
	v_mov_b32_dpp v121, v113 quad_perm:[1,0,3,2] row_mask:0xf bank_mask:0xf
	v_mov_b32_dpp v122, v114 quad_perm:[1,0,3,2] row_mask:0xf bank_mask:0xf
	v_mov_b32_dpp v123, v115 quad_perm:[1,0,3,2] row_mask:0xf bank_mask:0xf
	v_mov_b32_dpp v124, v116 quad_perm:[1,0,3,2] row_mask:0xf bank_mask:0xf
	v_mov_b32_dpp v125, v117 quad_perm:[1,0,3,2] row_mask:0xf bank_mask:0xf
	v_mov_b32_dpp v126, v118 quad_perm:[1,0,3,2] row_mask:0xf bank_mask:0xf
	v_mov_b32_dpp v127, v119 quad_perm:[1,0,3,2] row_mask:0xf bank_mask:0xf
	v_mul_f32_e32 v128, s28, v112
	v_mul_f32_e32 v129, s29, v113
	v_mul_f32_e32 v130, s30, v114
	v_mul_f32_e32 v131, s31, v115
	v_mul_f32_e32 v132, s34, v116
	v_mul_f32_e32 v133, s35, v117
	v_mul_f32_e32 v134, s36, v118
	v_mul_f32_e32 v135, s37, v119
	v_fmac_f32_e32 v128, v32, v120
	v_fmac_f32_e32 v129, v33, v121
	v_fmac_f32_e32 v130, v34, v122
	v_fmac_f32_e32 v131, v35, v123
	v_fmac_f32_e32 v132, v36, v124
	v_fmac_f32_e32 v133, v37, v125
	v_fmac_f32_e32 v134, v38, v126
	v_fmac_f32_e32 v135, v39, v127
	v_cndmask_b32_e32 v112, v112, v128, vcc
	v_cndmask_b32_e32 v113, v113, v129, vcc
	v_cndmask_b32_e32 v114, v114, v130, vcc
	v_cndmask_b32_e32 v115, v115, v131, vcc
	v_cndmask_b32_e32 v116, v116, v132, vcc
	v_cndmask_b32_e32 v117, v117, v133, vcc
	v_cndmask_b32_e32 v118, v118, v134, vcc
	v_cndmask_b32_e32 v119, v119, v135, vcc
	v_cvt_pk_bf16_f32 v136, v112, v113
	v_cvt_pk_bf16_f32 v137, v114, v115
	v_cvt_pk_bf16_f32 v138, v116, v117
	v_cvt_pk_bf16_f32 v139, v118, v119
	v_cndmask_b32_e64 v136, v136, v60, s[18:19]
	v_cndmask_b32_e64 v137, v137, v61, s[18:19]
	v_cndmask_b32_e64 v138, v138, v62, s[18:19]
	v_cndmask_b32_e64 v139, v139, v63, s[18:19]
	global_store_dwordx4 v8, v[136:139], s[12:13]
	s_add_u32 s6, s6, 0x200000
	s_addc_u32 s7, s7, 0
	s_add_u32 s12, s12, 0x80000
	s_addc_u32 s13, s13, 0
	s_waitcnt vmcnt(14)
	v_readlane_b32 s28, v11, 16
	v_readlane_b32 s38, v12, 16
	v_readlane_b32 s29, v11, 17
	v_readlane_b32 s39, v12, 17
	v_readlane_b32 s30, v11, 18
	v_readlane_b32 s40, v12, 18
	v_readlane_b32 s31, v11, 19
	v_readlane_b32 s41, v12, 19
	v_readlane_b32 s34, v11, 20
	v_readlane_b32 s42, v12, 20
	v_readlane_b32 s35, v11, 21
	v_readlane_b32 s43, v12, 21
	v_readlane_b32 s36, v11, 22
	v_readlane_b32 s44, v12, 22
	v_readlane_b32 s37, v11, 23
	v_readlane_b32 s45, v12, 23
	v_mul_f32_e32 v32, s38, v10
	v_mul_f32_e32 v33, s39, v10
	v_mul_f32_e32 v34, s40, v10
	v_mul_f32_e32 v35, s41, v10
	v_mul_f32_e32 v36, s42, v10
	v_mul_f32_e32 v37, s43, v10
	v_mul_f32_e32 v38, s44, v10
	v_mul_f32_e32 v39, s45, v10
	v_lshlrev_b32_e32 v112, 16, v64
	v_and_b32_e32 v113, 0xffff0000, v64
	v_lshlrev_b32_e32 v114, 16, v65
	v_and_b32_e32 v115, 0xffff0000, v65
	v_lshlrev_b32_e32 v116, 16, v66
	v_and_b32_e32 v117, 0xffff0000, v66
	v_lshlrev_b32_e32 v118, 16, v67
	v_and_b32_e32 v119, 0xffff0000, v67
	v_mul_f32_e32 v140, v112, v112
	v_mul_f32_e32 v141, v113, v113
	v_fmac_f32_e32 v140, v114, v114
	v_fmac_f32_e32 v141, v115, v115
	v_fmac_f32_e32 v140, v116, v116
	v_fmac_f32_e32 v141, v117, v117
	v_fmac_f32_e32 v140, v118, v118
	v_fmac_f32_e32 v141, v119, v119
	v_add_f32_e32 v140, v140, v141
	s_nop 1
	v_add_f32_dpp v140, v140, v140 quad_perm:[1,0,3,2] row_mask:0xf bank_mask:0xf bound_ctrl:1
	s_nop 1
	v_add_f32_dpp v140, v140, v140 quad_perm:[2,3,0,1] row_mask:0xf bank_mask:0xf bound_ctrl:1
	s_nop 1
	v_add_f32_dpp v140, v140, v140 row_half_mirror row_mask:0xf bank_mask:0xf bound_ctrl:1
	v_fma_f32 v141, v140, s10, v15
	v_rsq_f32_e32 v141, v141
	s_nop 0
	v_mul_f32_e32 v112, v112, v141
	v_mul_f32_e32 v113, v113, v141
	v_mul_f32_e32 v114, v114, v141
	v_mul_f32_e32 v115, v115, v141
	v_mul_f32_e32 v116, v116, v141
	v_mul_f32_e32 v117, v117, v141
	v_mul_f32_e32 v118, v118, v141
	v_mul_f32_e32 v119, v119, v141
	v_mul_f32_e32 v112, v112, v16
	v_mul_f32_e32 v113, v113, v17
	v_mul_f32_e32 v114, v114, v18
	v_mul_f32_e32 v115, v115, v19
	v_mul_f32_e32 v116, v116, v20
	v_mul_f32_e32 v117, v117, v21
	v_mul_f32_e32 v118, v118, v22
	v_mul_f32_e32 v119, v119, v23
	v_mov_b32_dpp v120, v112 quad_perm:[1,0,3,2] row_mask:0xf bank_mask:0xf
	v_mov_b32_dpp v121, v113 quad_perm:[1,0,3,2] row_mask:0xf bank_mask:0xf
	v_mov_b32_dpp v122, v114 quad_perm:[1,0,3,2] row_mask:0xf bank_mask:0xf
	v_mov_b32_dpp v123, v115 quad_perm:[1,0,3,2] row_mask:0xf bank_mask:0xf
	v_mov_b32_dpp v124, v116 quad_perm:[1,0,3,2] row_mask:0xf bank_mask:0xf
	v_mov_b32_dpp v125, v117 quad_perm:[1,0,3,2] row_mask:0xf bank_mask:0xf
	v_mov_b32_dpp v126, v118 quad_perm:[1,0,3,2] row_mask:0xf bank_mask:0xf
	v_mov_b32_dpp v127, v119 quad_perm:[1,0,3,2] row_mask:0xf bank_mask:0xf
	v_mul_f32_e32 v128, s28, v112
	v_mul_f32_e32 v129, s29, v113
	v_mul_f32_e32 v130, s30, v114
	v_mul_f32_e32 v131, s31, v115
	v_mul_f32_e32 v132, s34, v116
	v_mul_f32_e32 v133, s35, v117
	v_mul_f32_e32 v134, s36, v118
	v_mul_f32_e32 v135, s37, v119
	v_fmac_f32_e32 v128, v32, v120
	v_fmac_f32_e32 v129, v33, v121
	v_fmac_f32_e32 v130, v34, v122
	v_fmac_f32_e32 v131, v35, v123
	v_fmac_f32_e32 v132, v36, v124
	v_fmac_f32_e32 v133, v37, v125
	v_fmac_f32_e32 v134, v38, v126
	v_fmac_f32_e32 v135, v39, v127
	v_cndmask_b32_e32 v112, v112, v128, vcc
	v_cndmask_b32_e32 v113, v113, v129, vcc
	v_cndmask_b32_e32 v114, v114, v130, vcc
	v_cndmask_b32_e32 v115, v115, v131, vcc
	v_cndmask_b32_e32 v116, v116, v132, vcc
	v_cndmask_b32_e32 v117, v117, v133, vcc
	v_cndmask_b32_e32 v118, v118, v134, vcc
	v_cndmask_b32_e32 v119, v119, v135, vcc
	v_mul_f32_e32 v112, 0x3e38aa3b, v112
	v_mul_f32_e32 v113, 0x3e38aa3b, v113
	v_mul_f32_e32 v114, 0x3e38aa3b, v114
	v_mul_f32_e32 v115, 0x3e38aa3b, v115
	v_mul_f32_e32 v116, 0x3e38aa3b, v116
	v_mul_f32_e32 v117, 0x3e38aa3b, v117
	v_mul_f32_e32 v118, 0x3e38aa3b, v118
	v_mul_f32_e32 v119, 0x3e38aa3b, v119
	v_cvt_pk_bf16_f32 v136, v112, v113
	v_cvt_pk_bf16_f32 v137, v114, v115
	v_cvt_pk_bf16_f32 v138, v116, v117
	v_cvt_pk_bf16_f32 v139, v118, v119
	global_store_dwordx4 v7, v[136:139], s[6:7]
	s_nop 1
	v_lshlrev_b32_e32 v112, 16, v68
	v_and_b32_e32 v113, 0xffff0000, v68
	v_lshlrev_b32_e32 v114, 16, v69
	v_and_b32_e32 v115, 0xffff0000, v69
	v_lshlrev_b32_e32 v116, 16, v70
	v_and_b32_e32 v117, 0xffff0000, v70
	v_lshlrev_b32_e32 v118, 16, v71
	v_and_b32_e32 v119, 0xffff0000, v71
	v_mul_f32_e32 v140, v112, v112
	v_mul_f32_e32 v141, v113, v113
	v_fmac_f32_e32 v140, v114, v114
	v_fmac_f32_e32 v141, v115, v115
	v_fmac_f32_e32 v140, v116, v116
	v_fmac_f32_e32 v141, v117, v117
	v_fmac_f32_e32 v140, v118, v118
	v_fmac_f32_e32 v141, v119, v119
	v_add_f32_e32 v140, v140, v141
	s_nop 1
	v_add_f32_dpp v140, v140, v140 quad_perm:[1,0,3,2] row_mask:0xf bank_mask:0xf bound_ctrl:1
	s_nop 1
	v_add_f32_dpp v140, v140, v140 quad_perm:[2,3,0,1] row_mask:0xf bank_mask:0xf bound_ctrl:1
	s_nop 1
	v_add_f32_dpp v140, v140, v140 row_half_mirror row_mask:0xf bank_mask:0xf bound_ctrl:1
	v_fma_f32 v141, v140, s10, v15
	v_rsq_f32_e32 v141, v141
	s_nop 0
	v_mul_f32_e32 v112, v112, v141
	v_mul_f32_e32 v113, v113, v141
	v_mul_f32_e32 v114, v114, v141
	v_mul_f32_e32 v115, v115, v141
	v_mul_f32_e32 v116, v116, v141
	v_mul_f32_e32 v117, v117, v141
	v_mul_f32_e32 v118, v118, v141
	v_mul_f32_e32 v119, v119, v141
	v_mul_f32_e32 v112, v112, v24
	v_mul_f32_e32 v113, v113, v25
	v_mul_f32_e32 v114, v114, v26
	v_mul_f32_e32 v115, v115, v27
	v_mul_f32_e32 v116, v116, v28
	v_mul_f32_e32 v117, v117, v29
	v_mul_f32_e32 v118, v118, v30
	v_mul_f32_e32 v119, v119, v31
	v_mov_b32_dpp v120, v112 quad_perm:[1,0,3,2] row_mask:0xf bank_mask:0xf
	v_mov_b32_dpp v121, v113 quad_perm:[1,0,3,2] row_mask:0xf bank_mask:0xf
	v_mov_b32_dpp v122, v114 quad_perm:[1,0,3,2] row_mask:0xf bank_mask:0xf
	v_mov_b32_dpp v123, v115 quad_perm:[1,0,3,2] row_mask:0xf bank_mask:0xf
	v_mov_b32_dpp v124, v116 quad_perm:[1,0,3,2] row_mask:0xf bank_mask:0xf
	v_mov_b32_dpp v125, v117 quad_perm:[1,0,3,2] row_mask:0xf bank_mask:0xf
	v_mov_b32_dpp v126, v118 quad_perm:[1,0,3,2] row_mask:0xf bank_mask:0xf
	v_mov_b32_dpp v127, v119 quad_perm:[1,0,3,2] row_mask:0xf bank_mask:0xf
	v_mul_f32_e32 v128, s28, v112
	v_mul_f32_e32 v129, s29, v113
	v_mul_f32_e32 v130, s30, v114
	v_mul_f32_e32 v131, s31, v115
	v_mul_f32_e32 v132, s34, v116
	v_mul_f32_e32 v133, s35, v117
	v_mul_f32_e32 v134, s36, v118
	v_mul_f32_e32 v135, s37, v119
	v_fmac_f32_e32 v128, v32, v120
	v_fmac_f32_e32 v129, v33, v121
	v_fmac_f32_e32 v130, v34, v122
	v_fmac_f32_e32 v131, v35, v123
	v_fmac_f32_e32 v132, v36, v124
	v_fmac_f32_e32 v133, v37, v125
	v_fmac_f32_e32 v134, v38, v126
	v_fmac_f32_e32 v135, v39, v127
	v_cndmask_b32_e32 v112, v112, v128, vcc
	v_cndmask_b32_e32 v113, v113, v129, vcc
	v_cndmask_b32_e32 v114, v114, v130, vcc
	v_cndmask_b32_e32 v115, v115, v131, vcc
	v_cndmask_b32_e32 v116, v116, v132, vcc
	v_cndmask_b32_e32 v117, v117, v133, vcc
	v_cndmask_b32_e32 v118, v118, v134, vcc
	v_cndmask_b32_e32 v119, v119, v135, vcc
	v_cvt_pk_bf16_f32 v136, v112, v113
	v_cvt_pk_bf16_f32 v137, v114, v115
	v_cvt_pk_bf16_f32 v138, v116, v117
	v_cvt_pk_bf16_f32 v139, v118, v119
	v_cndmask_b32_e64 v136, v136, v68, s[18:19]
	v_cndmask_b32_e64 v137, v137, v69, s[18:19]
	v_cndmask_b32_e64 v138, v138, v70, s[18:19]
	v_cndmask_b32_e64 v139, v139, v71, s[18:19]
	global_store_dwordx4 v8, v[136:139], s[12:13]
	s_add_u32 s6, s6, 0x200000
	s_addc_u32 s7, s7, 0
	s_add_u32 s12, s12, 0x80000
	s_addc_u32 s13, s13, 0
	s_waitcnt vmcnt(14)
	v_readlane_b32 s28, v11, 24
	v_readlane_b32 s38, v12, 24
	v_readlane_b32 s29, v11, 25
	v_readlane_b32 s39, v12, 25
	v_readlane_b32 s30, v11, 26
	v_readlane_b32 s40, v12, 26
	v_readlane_b32 s31, v11, 27
	v_readlane_b32 s41, v12, 27
	v_readlane_b32 s34, v11, 28
	v_readlane_b32 s42, v12, 28
	v_readlane_b32 s35, v11, 29
	v_readlane_b32 s43, v12, 29
	v_readlane_b32 s36, v11, 30
	v_readlane_b32 s44, v12, 30
	v_readlane_b32 s37, v11, 31
	v_readlane_b32 s45, v12, 31
	v_mul_f32_e32 v32, s38, v10
	v_mul_f32_e32 v33, s39, v10
	v_mul_f32_e32 v34, s40, v10
	v_mul_f32_e32 v35, s41, v10
	v_mul_f32_e32 v36, s42, v10
	v_mul_f32_e32 v37, s43, v10
	v_mul_f32_e32 v38, s44, v10
	v_mul_f32_e32 v39, s45, v10
	v_lshlrev_b32_e32 v112, 16, v72
	v_and_b32_e32 v113, 0xffff0000, v72
	v_lshlrev_b32_e32 v114, 16, v73
	v_and_b32_e32 v115, 0xffff0000, v73
	v_lshlrev_b32_e32 v116, 16, v74
	v_and_b32_e32 v117, 0xffff0000, v74
	v_lshlrev_b32_e32 v118, 16, v75
	v_and_b32_e32 v119, 0xffff0000, v75
	v_mul_f32_e32 v140, v112, v112
	v_mul_f32_e32 v141, v113, v113
	v_fmac_f32_e32 v140, v114, v114
	v_fmac_f32_e32 v141, v115, v115
	v_fmac_f32_e32 v140, v116, v116
	v_fmac_f32_e32 v141, v117, v117
	v_fmac_f32_e32 v140, v118, v118
	v_fmac_f32_e32 v141, v119, v119
	v_add_f32_e32 v140, v140, v141
	s_nop 1
	v_add_f32_dpp v140, v140, v140 quad_perm:[1,0,3,2] row_mask:0xf bank_mask:0xf bound_ctrl:1
	s_nop 1
	v_add_f32_dpp v140, v140, v140 quad_perm:[2,3,0,1] row_mask:0xf bank_mask:0xf bound_ctrl:1
	s_nop 1
	v_add_f32_dpp v140, v140, v140 row_half_mirror row_mask:0xf bank_mask:0xf bound_ctrl:1
	v_fma_f32 v141, v140, s10, v15
	v_rsq_f32_e32 v141, v141
	s_nop 0
	v_mul_f32_e32 v112, v112, v141
	v_mul_f32_e32 v113, v113, v141
	v_mul_f32_e32 v114, v114, v141
	v_mul_f32_e32 v115, v115, v141
	v_mul_f32_e32 v116, v116, v141
	v_mul_f32_e32 v117, v117, v141
	v_mul_f32_e32 v118, v118, v141
	v_mul_f32_e32 v119, v119, v141
	v_mul_f32_e32 v112, v112, v16
	v_mul_f32_e32 v113, v113, v17
	v_mul_f32_e32 v114, v114, v18
	v_mul_f32_e32 v115, v115, v19
	v_mul_f32_e32 v116, v116, v20
	v_mul_f32_e32 v117, v117, v21
	v_mul_f32_e32 v118, v118, v22
	v_mul_f32_e32 v119, v119, v23
	v_mov_b32_dpp v120, v112 quad_perm:[1,0,3,2] row_mask:0xf bank_mask:0xf
	v_mov_b32_dpp v121, v113 quad_perm:[1,0,3,2] row_mask:0xf bank_mask:0xf
	v_mov_b32_dpp v122, v114 quad_perm:[1,0,3,2] row_mask:0xf bank_mask:0xf
	v_mov_b32_dpp v123, v115 quad_perm:[1,0,3,2] row_mask:0xf bank_mask:0xf
	v_mov_b32_dpp v124, v116 quad_perm:[1,0,3,2] row_mask:0xf bank_mask:0xf
	v_mov_b32_dpp v125, v117 quad_perm:[1,0,3,2] row_mask:0xf bank_mask:0xf
	v_mov_b32_dpp v126, v118 quad_perm:[1,0,3,2] row_mask:0xf bank_mask:0xf
	v_mov_b32_dpp v127, v119 quad_perm:[1,0,3,2] row_mask:0xf bank_mask:0xf
	v_mul_f32_e32 v128, s28, v112
	v_mul_f32_e32 v129, s29, v113
	v_mul_f32_e32 v130, s30, v114
	v_mul_f32_e32 v131, s31, v115
	v_mul_f32_e32 v132, s34, v116
	v_mul_f32_e32 v133, s35, v117
	v_mul_f32_e32 v134, s36, v118
	v_mul_f32_e32 v135, s37, v119
	v_fmac_f32_e32 v128, v32, v120
	v_fmac_f32_e32 v129, v33, v121
	v_fmac_f32_e32 v130, v34, v122
	v_fmac_f32_e32 v131, v35, v123
	v_fmac_f32_e32 v132, v36, v124
	v_fmac_f32_e32 v133, v37, v125
	v_fmac_f32_e32 v134, v38, v126
	v_fmac_f32_e32 v135, v39, v127
	v_cndmask_b32_e32 v112, v112, v128, vcc
	v_cndmask_b32_e32 v113, v113, v129, vcc
	v_cndmask_b32_e32 v114, v114, v130, vcc
	v_cndmask_b32_e32 v115, v115, v131, vcc
	v_cndmask_b32_e32 v116, v116, v132, vcc
	v_cndmask_b32_e32 v117, v117, v133, vcc
	v_cndmask_b32_e32 v118, v118, v134, vcc
	v_cndmask_b32_e32 v119, v119, v135, vcc
	v_mul_f32_e32 v112, 0x3e38aa3b, v112
	v_mul_f32_e32 v113, 0x3e38aa3b, v113
	v_mul_f32_e32 v114, 0x3e38aa3b, v114
	v_mul_f32_e32 v115, 0x3e38aa3b, v115
	v_mul_f32_e32 v116, 0x3e38aa3b, v116
	v_mul_f32_e32 v117, 0x3e38aa3b, v117
	v_mul_f32_e32 v118, 0x3e38aa3b, v118
	v_mul_f32_e32 v119, 0x3e38aa3b, v119
	v_cvt_pk_bf16_f32 v136, v112, v113
	v_cvt_pk_bf16_f32 v137, v114, v115
	v_cvt_pk_bf16_f32 v138, v116, v117
	v_cvt_pk_bf16_f32 v139, v118, v119
	global_store_dwordx4 v7, v[136:139], s[6:7]
	s_nop 1
	v_lshlrev_b32_e32 v112, 16, v76
	v_and_b32_e32 v113, 0xffff0000, v76
	v_lshlrev_b32_e32 v114, 16, v77
	v_and_b32_e32 v115, 0xffff0000, v77
	v_lshlrev_b32_e32 v116, 16, v78
	v_and_b32_e32 v117, 0xffff0000, v78
	v_lshlrev_b32_e32 v118, 16, v79
	v_and_b32_e32 v119, 0xffff0000, v79
	v_mul_f32_e32 v140, v112, v112
	v_mul_f32_e32 v141, v113, v113
	v_fmac_f32_e32 v140, v114, v114
	v_fmac_f32_e32 v141, v115, v115
	v_fmac_f32_e32 v140, v116, v116
	v_fmac_f32_e32 v141, v117, v117
	v_fmac_f32_e32 v140, v118, v118
	v_fmac_f32_e32 v141, v119, v119
	v_add_f32_e32 v140, v140, v141
	s_nop 1
	v_add_f32_dpp v140, v140, v140 quad_perm:[1,0,3,2] row_mask:0xf bank_mask:0xf bound_ctrl:1
	s_nop 1
	v_add_f32_dpp v140, v140, v140 quad_perm:[2,3,0,1] row_mask:0xf bank_mask:0xf bound_ctrl:1
	s_nop 1
	v_add_f32_dpp v140, v140, v140 row_half_mirror row_mask:0xf bank_mask:0xf bound_ctrl:1
	v_fma_f32 v141, v140, s10, v15
	v_rsq_f32_e32 v141, v141
	s_nop 0
	v_mul_f32_e32 v112, v112, v141
	v_mul_f32_e32 v113, v113, v141
	v_mul_f32_e32 v114, v114, v141
	v_mul_f32_e32 v115, v115, v141
	v_mul_f32_e32 v116, v116, v141
	v_mul_f32_e32 v117, v117, v141
	v_mul_f32_e32 v118, v118, v141
	v_mul_f32_e32 v119, v119, v141
	v_mul_f32_e32 v112, v112, v24
	v_mul_f32_e32 v113, v113, v25
	v_mul_f32_e32 v114, v114, v26
	v_mul_f32_e32 v115, v115, v27
	v_mul_f32_e32 v116, v116, v28
	v_mul_f32_e32 v117, v117, v29
	v_mul_f32_e32 v118, v118, v30
	v_mul_f32_e32 v119, v119, v31
	v_mov_b32_dpp v120, v112 quad_perm:[1,0,3,2] row_mask:0xf bank_mask:0xf
	v_mov_b32_dpp v121, v113 quad_perm:[1,0,3,2] row_mask:0xf bank_mask:0xf
	v_mov_b32_dpp v122, v114 quad_perm:[1,0,3,2] row_mask:0xf bank_mask:0xf
	v_mov_b32_dpp v123, v115 quad_perm:[1,0,3,2] row_mask:0xf bank_mask:0xf
	v_mov_b32_dpp v124, v116 quad_perm:[1,0,3,2] row_mask:0xf bank_mask:0xf
	v_mov_b32_dpp v125, v117 quad_perm:[1,0,3,2] row_mask:0xf bank_mask:0xf
	v_mov_b32_dpp v126, v118 quad_perm:[1,0,3,2] row_mask:0xf bank_mask:0xf
	v_mov_b32_dpp v127, v119 quad_perm:[1,0,3,2] row_mask:0xf bank_mask:0xf
	v_mul_f32_e32 v128, s28, v112
	v_mul_f32_e32 v129, s29, v113
	v_mul_f32_e32 v130, s30, v114
	v_mul_f32_e32 v131, s31, v115
	v_mul_f32_e32 v132, s34, v116
	v_mul_f32_e32 v133, s35, v117
	v_mul_f32_e32 v134, s36, v118
	v_mul_f32_e32 v135, s37, v119
	v_fmac_f32_e32 v128, v32, v120
	v_fmac_f32_e32 v129, v33, v121
	v_fmac_f32_e32 v130, v34, v122
	v_fmac_f32_e32 v131, v35, v123
	v_fmac_f32_e32 v132, v36, v124
	v_fmac_f32_e32 v133, v37, v125
	v_fmac_f32_e32 v134, v38, v126
	v_fmac_f32_e32 v135, v39, v127
	v_cndmask_b32_e32 v112, v112, v128, vcc
	v_cndmask_b32_e32 v113, v113, v129, vcc
	v_cndmask_b32_e32 v114, v114, v130, vcc
	v_cndmask_b32_e32 v115, v115, v131, vcc
	v_cndmask_b32_e32 v116, v116, v132, vcc
	v_cndmask_b32_e32 v117, v117, v133, vcc
	v_cndmask_b32_e32 v118, v118, v134, vcc
	v_cndmask_b32_e32 v119, v119, v135, vcc
	v_cvt_pk_bf16_f32 v136, v112, v113
	v_cvt_pk_bf16_f32 v137, v114, v115
	v_cvt_pk_bf16_f32 v138, v116, v117
	v_cvt_pk_bf16_f32 v139, v118, v119
	v_cndmask_b32_e64 v136, v136, v76, s[18:19]
	v_cndmask_b32_e64 v137, v137, v77, s[18:19]
	v_cndmask_b32_e64 v138, v138, v78, s[18:19]
	v_cndmask_b32_e64 v139, v139, v79, s[18:19]
	global_store_dwordx4 v8, v[136:139], s[12:13]
	s_add_u32 s6, s6, 0x200000
	s_addc_u32 s7, s7, 0
	s_add_u32 s12, s12, 0x80000
	s_addc_u32 s13, s13, 0
	s_waitcnt vmcnt(14)
	v_readlane_b32 s28, v11, 32
	v_readlane_b32 s38, v12, 32
	v_readlane_b32 s29, v11, 33
	v_readlane_b32 s39, v12, 33
	v_readlane_b32 s30, v11, 34
	v_readlane_b32 s40, v12, 34
	v_readlane_b32 s31, v11, 35
	v_readlane_b32 s41, v12, 35
	v_readlane_b32 s34, v11, 36
	v_readlane_b32 s42, v12, 36
	v_readlane_b32 s35, v11, 37
	v_readlane_b32 s43, v12, 37
	v_readlane_b32 s36, v11, 38
	v_readlane_b32 s44, v12, 38
	v_readlane_b32 s37, v11, 39
	v_readlane_b32 s45, v12, 39
	v_mul_f32_e32 v32, s38, v10
	v_mul_f32_e32 v33, s39, v10
	v_mul_f32_e32 v34, s40, v10
	v_mul_f32_e32 v35, s41, v10
	v_mul_f32_e32 v36, s42, v10
	v_mul_f32_e32 v37, s43, v10
	v_mul_f32_e32 v38, s44, v10
	v_mul_f32_e32 v39, s45, v10
	v_lshlrev_b32_e32 v112, 16, v80
	v_and_b32_e32 v113, 0xffff0000, v80
	v_lshlrev_b32_e32 v114, 16, v81
	v_and_b32_e32 v115, 0xffff0000, v81
	v_lshlrev_b32_e32 v116, 16, v82
	v_and_b32_e32 v117, 0xffff0000, v82
	v_lshlrev_b32_e32 v118, 16, v83
	v_and_b32_e32 v119, 0xffff0000, v83
	v_mul_f32_e32 v140, v112, v112
	v_mul_f32_e32 v141, v113, v113
	v_fmac_f32_e32 v140, v114, v114
	v_fmac_f32_e32 v141, v115, v115
	v_fmac_f32_e32 v140, v116, v116
	v_fmac_f32_e32 v141, v117, v117
	v_fmac_f32_e32 v140, v118, v118
	v_fmac_f32_e32 v141, v119, v119
	v_add_f32_e32 v140, v140, v141
	s_nop 1
	v_add_f32_dpp v140, v140, v140 quad_perm:[1,0,3,2] row_mask:0xf bank_mask:0xf bound_ctrl:1
	s_nop 1
	v_add_f32_dpp v140, v140, v140 quad_perm:[2,3,0,1] row_mask:0xf bank_mask:0xf bound_ctrl:1
	s_nop 1
	v_add_f32_dpp v140, v140, v140 row_half_mirror row_mask:0xf bank_mask:0xf bound_ctrl:1
	v_fma_f32 v141, v140, s10, v15
	v_rsq_f32_e32 v141, v141
	s_nop 0
	v_mul_f32_e32 v112, v112, v141
	v_mul_f32_e32 v113, v113, v141
	v_mul_f32_e32 v114, v114, v141
	v_mul_f32_e32 v115, v115, v141
	v_mul_f32_e32 v116, v116, v141
	v_mul_f32_e32 v117, v117, v141
	v_mul_f32_e32 v118, v118, v141
	v_mul_f32_e32 v119, v119, v141
	v_mul_f32_e32 v112, v112, v16
	v_mul_f32_e32 v113, v113, v17
	v_mul_f32_e32 v114, v114, v18
	v_mul_f32_e32 v115, v115, v19
	v_mul_f32_e32 v116, v116, v20
	v_mul_f32_e32 v117, v117, v21
	v_mul_f32_e32 v118, v118, v22
	v_mul_f32_e32 v119, v119, v23
	v_mov_b32_dpp v120, v112 quad_perm:[1,0,3,2] row_mask:0xf bank_mask:0xf
	v_mov_b32_dpp v121, v113 quad_perm:[1,0,3,2] row_mask:0xf bank_mask:0xf
	v_mov_b32_dpp v122, v114 quad_perm:[1,0,3,2] row_mask:0xf bank_mask:0xf
	v_mov_b32_dpp v123, v115 quad_perm:[1,0,3,2] row_mask:0xf bank_mask:0xf
	v_mov_b32_dpp v124, v116 quad_perm:[1,0,3,2] row_mask:0xf bank_mask:0xf
	v_mov_b32_dpp v125, v117 quad_perm:[1,0,3,2] row_mask:0xf bank_mask:0xf
	v_mov_b32_dpp v126, v118 quad_perm:[1,0,3,2] row_mask:0xf bank_mask:0xf
	v_mov_b32_dpp v127, v119 quad_perm:[1,0,3,2] row_mask:0xf bank_mask:0xf
	v_mul_f32_e32 v128, s28, v112
	v_mul_f32_e32 v129, s29, v113
	v_mul_f32_e32 v130, s30, v114
	v_mul_f32_e32 v131, s31, v115
	v_mul_f32_e32 v132, s34, v116
	v_mul_f32_e32 v133, s35, v117
	v_mul_f32_e32 v134, s36, v118
	v_mul_f32_e32 v135, s37, v119
	v_fmac_f32_e32 v128, v32, v120
	v_fmac_f32_e32 v129, v33, v121
	v_fmac_f32_e32 v130, v34, v122
	v_fmac_f32_e32 v131, v35, v123
	v_fmac_f32_e32 v132, v36, v124
	v_fmac_f32_e32 v133, v37, v125
	v_fmac_f32_e32 v134, v38, v126
	v_fmac_f32_e32 v135, v39, v127
	v_cndmask_b32_e32 v112, v112, v128, vcc
	v_cndmask_b32_e32 v113, v113, v129, vcc
	v_cndmask_b32_e32 v114, v114, v130, vcc
	v_cndmask_b32_e32 v115, v115, v131, vcc
	v_cndmask_b32_e32 v116, v116, v132, vcc
	v_cndmask_b32_e32 v117, v117, v133, vcc
	v_cndmask_b32_e32 v118, v118, v134, vcc
	v_cndmask_b32_e32 v119, v119, v135, vcc
	v_mul_f32_e32 v112, 0x3e38aa3b, v112
	v_mul_f32_e32 v113, 0x3e38aa3b, v113
	v_mul_f32_e32 v114, 0x3e38aa3b, v114
	v_mul_f32_e32 v115, 0x3e38aa3b, v115
	v_mul_f32_e32 v116, 0x3e38aa3b, v116
	v_mul_f32_e32 v117, 0x3e38aa3b, v117
	v_mul_f32_e32 v118, 0x3e38aa3b, v118
	v_mul_f32_e32 v119, 0x3e38aa3b, v119
	v_cvt_pk_bf16_f32 v136, v112, v113
	v_cvt_pk_bf16_f32 v137, v114, v115
	v_cvt_pk_bf16_f32 v138, v116, v117
	v_cvt_pk_bf16_f32 v139, v118, v119
	global_store_dwordx4 v7, v[136:139], s[6:7]
	s_nop 1
	v_lshlrev_b32_e32 v112, 16, v84
	v_and_b32_e32 v113, 0xffff0000, v84
	v_lshlrev_b32_e32 v114, 16, v85
	v_and_b32_e32 v115, 0xffff0000, v85
	v_lshlrev_b32_e32 v116, 16, v86
	v_and_b32_e32 v117, 0xffff0000, v86
	v_lshlrev_b32_e32 v118, 16, v87
	v_and_b32_e32 v119, 0xffff0000, v87
	v_mul_f32_e32 v140, v112, v112
	v_mul_f32_e32 v141, v113, v113
	v_fmac_f32_e32 v140, v114, v114
	v_fmac_f32_e32 v141, v115, v115
	v_fmac_f32_e32 v140, v116, v116
	v_fmac_f32_e32 v141, v117, v117
	v_fmac_f32_e32 v140, v118, v118
	v_fmac_f32_e32 v141, v119, v119
	v_add_f32_e32 v140, v140, v141
	s_nop 1
	v_add_f32_dpp v140, v140, v140 quad_perm:[1,0,3,2] row_mask:0xf bank_mask:0xf bound_ctrl:1
	s_nop 1
	v_add_f32_dpp v140, v140, v140 quad_perm:[2,3,0,1] row_mask:0xf bank_mask:0xf bound_ctrl:1
	s_nop 1
	v_add_f32_dpp v140, v140, v140 row_half_mirror row_mask:0xf bank_mask:0xf bound_ctrl:1
	v_fma_f32 v141, v140, s10, v15
	v_rsq_f32_e32 v141, v141
	s_nop 0
	v_mul_f32_e32 v112, v112, v141
	v_mul_f32_e32 v113, v113, v141
	v_mul_f32_e32 v114, v114, v141
	v_mul_f32_e32 v115, v115, v141
	v_mul_f32_e32 v116, v116, v141
	v_mul_f32_e32 v117, v117, v141
	v_mul_f32_e32 v118, v118, v141
	v_mul_f32_e32 v119, v119, v141
	v_mul_f32_e32 v112, v112, v24
	v_mul_f32_e32 v113, v113, v25
	v_mul_f32_e32 v114, v114, v26
	v_mul_f32_e32 v115, v115, v27
	v_mul_f32_e32 v116, v116, v28
	v_mul_f32_e32 v117, v117, v29
	v_mul_f32_e32 v118, v118, v30
	v_mul_f32_e32 v119, v119, v31
	v_mov_b32_dpp v120, v112 quad_perm:[1,0,3,2] row_mask:0xf bank_mask:0xf
	v_mov_b32_dpp v121, v113 quad_perm:[1,0,3,2] row_mask:0xf bank_mask:0xf
	v_mov_b32_dpp v122, v114 quad_perm:[1,0,3,2] row_mask:0xf bank_mask:0xf
	v_mov_b32_dpp v123, v115 quad_perm:[1,0,3,2] row_mask:0xf bank_mask:0xf
	v_mov_b32_dpp v124, v116 quad_perm:[1,0,3,2] row_mask:0xf bank_mask:0xf
	v_mov_b32_dpp v125, v117 quad_perm:[1,0,3,2] row_mask:0xf bank_mask:0xf
	v_mov_b32_dpp v126, v118 quad_perm:[1,0,3,2] row_mask:0xf bank_mask:0xf
	v_mov_b32_dpp v127, v119 quad_perm:[1,0,3,2] row_mask:0xf bank_mask:0xf
	v_mul_f32_e32 v128, s28, v112
	v_mul_f32_e32 v129, s29, v113
	v_mul_f32_e32 v130, s30, v114
	v_mul_f32_e32 v131, s31, v115
	v_mul_f32_e32 v132, s34, v116
	v_mul_f32_e32 v133, s35, v117
	v_mul_f32_e32 v134, s36, v118
	v_mul_f32_e32 v135, s37, v119
	v_fmac_f32_e32 v128, v32, v120
	v_fmac_f32_e32 v129, v33, v121
	v_fmac_f32_e32 v130, v34, v122
	v_fmac_f32_e32 v131, v35, v123
	v_fmac_f32_e32 v132, v36, v124
	v_fmac_f32_e32 v133, v37, v125
	v_fmac_f32_e32 v134, v38, v126
	v_fmac_f32_e32 v135, v39, v127
	v_cndmask_b32_e32 v112, v112, v128, vcc
	v_cndmask_b32_e32 v113, v113, v129, vcc
	v_cndmask_b32_e32 v114, v114, v130, vcc
	v_cndmask_b32_e32 v115, v115, v131, vcc
	v_cndmask_b32_e32 v116, v116, v132, vcc
	v_cndmask_b32_e32 v117, v117, v133, vcc
	v_cndmask_b32_e32 v118, v118, v134, vcc
	v_cndmask_b32_e32 v119, v119, v135, vcc
	v_cvt_pk_bf16_f32 v136, v112, v113
	v_cvt_pk_bf16_f32 v137, v114, v115
	v_cvt_pk_bf16_f32 v138, v116, v117
	v_cvt_pk_bf16_f32 v139, v118, v119
	v_cndmask_b32_e64 v136, v136, v84, s[18:19]
	v_cndmask_b32_e64 v137, v137, v85, s[18:19]
	v_cndmask_b32_e64 v138, v138, v86, s[18:19]
	v_cndmask_b32_e64 v139, v139, v87, s[18:19]
	global_store_dwordx4 v8, v[136:139], s[12:13]
	s_add_u32 s6, s6, 0x200000
	s_addc_u32 s7, s7, 0
	s_add_u32 s12, s12, 0x80000
	s_addc_u32 s13, s13, 0
	s_waitcnt vmcnt(14)
	v_readlane_b32 s28, v11, 40
	v_readlane_b32 s38, v12, 40
	v_readlane_b32 s29, v11, 41
	v_readlane_b32 s39, v12, 41
	v_readlane_b32 s30, v11, 42
	v_readlane_b32 s40, v12, 42
	v_readlane_b32 s31, v11, 43
	v_readlane_b32 s41, v12, 43
	v_readlane_b32 s34, v11, 44
	v_readlane_b32 s42, v12, 44
	v_readlane_b32 s35, v11, 45
	v_readlane_b32 s43, v12, 45
	v_readlane_b32 s36, v11, 46
	v_readlane_b32 s44, v12, 46
	v_readlane_b32 s37, v11, 47
	v_readlane_b32 s45, v12, 47
	v_mul_f32_e32 v32, s38, v10
	v_mul_f32_e32 v33, s39, v10
	v_mul_f32_e32 v34, s40, v10
	v_mul_f32_e32 v35, s41, v10
	v_mul_f32_e32 v36, s42, v10
	v_mul_f32_e32 v37, s43, v10
	v_mul_f32_e32 v38, s44, v10
	v_mul_f32_e32 v39, s45, v10
	v_lshlrev_b32_e32 v112, 16, v88
	v_and_b32_e32 v113, 0xffff0000, v88
	v_lshlrev_b32_e32 v114, 16, v89
	v_and_b32_e32 v115, 0xffff0000, v89
	v_lshlrev_b32_e32 v116, 16, v90
	v_and_b32_e32 v117, 0xffff0000, v90
	v_lshlrev_b32_e32 v118, 16, v91
	v_and_b32_e32 v119, 0xffff0000, v91
	v_mul_f32_e32 v140, v112, v112
	v_mul_f32_e32 v141, v113, v113
	v_fmac_f32_e32 v140, v114, v114
	v_fmac_f32_e32 v141, v115, v115
	v_fmac_f32_e32 v140, v116, v116
	v_fmac_f32_e32 v141, v117, v117
	v_fmac_f32_e32 v140, v118, v118
	v_fmac_f32_e32 v141, v119, v119
	v_add_f32_e32 v140, v140, v141
	s_nop 1
	v_add_f32_dpp v140, v140, v140 quad_perm:[1,0,3,2] row_mask:0xf bank_mask:0xf bound_ctrl:1
	s_nop 1
	v_add_f32_dpp v140, v140, v140 quad_perm:[2,3,0,1] row_mask:0xf bank_mask:0xf bound_ctrl:1
	s_nop 1
	v_add_f32_dpp v140, v140, v140 row_half_mirror row_mask:0xf bank_mask:0xf bound_ctrl:1
	v_fma_f32 v141, v140, s10, v15
	v_rsq_f32_e32 v141, v141
	s_nop 0
	v_mul_f32_e32 v112, v112, v141
	v_mul_f32_e32 v113, v113, v141
	v_mul_f32_e32 v114, v114, v141
	v_mul_f32_e32 v115, v115, v141
	v_mul_f32_e32 v116, v116, v141
	v_mul_f32_e32 v117, v117, v141
	v_mul_f32_e32 v118, v118, v141
	v_mul_f32_e32 v119, v119, v141
	v_mul_f32_e32 v112, v112, v16
	v_mul_f32_e32 v113, v113, v17
	v_mul_f32_e32 v114, v114, v18
	v_mul_f32_e32 v115, v115, v19
	v_mul_f32_e32 v116, v116, v20
	v_mul_f32_e32 v117, v117, v21
	v_mul_f32_e32 v118, v118, v22
	v_mul_f32_e32 v119, v119, v23
	v_mov_b32_dpp v120, v112 quad_perm:[1,0,3,2] row_mask:0xf bank_mask:0xf
	v_mov_b32_dpp v121, v113 quad_perm:[1,0,3,2] row_mask:0xf bank_mask:0xf
	v_mov_b32_dpp v122, v114 quad_perm:[1,0,3,2] row_mask:0xf bank_mask:0xf
	v_mov_b32_dpp v123, v115 quad_perm:[1,0,3,2] row_mask:0xf bank_mask:0xf
	v_mov_b32_dpp v124, v116 quad_perm:[1,0,3,2] row_mask:0xf bank_mask:0xf
	v_mov_b32_dpp v125, v117 quad_perm:[1,0,3,2] row_mask:0xf bank_mask:0xf
	v_mov_b32_dpp v126, v118 quad_perm:[1,0,3,2] row_mask:0xf bank_mask:0xf
	v_mov_b32_dpp v127, v119 quad_perm:[1,0,3,2] row_mask:0xf bank_mask:0xf
	v_mul_f32_e32 v128, s28, v112
	v_mul_f32_e32 v129, s29, v113
	v_mul_f32_e32 v130, s30, v114
	v_mul_f32_e32 v131, s31, v115
	v_mul_f32_e32 v132, s34, v116
	v_mul_f32_e32 v133, s35, v117
	v_mul_f32_e32 v134, s36, v118
	v_mul_f32_e32 v135, s37, v119
	v_fmac_f32_e32 v128, v32, v120
	v_fmac_f32_e32 v129, v33, v121
	v_fmac_f32_e32 v130, v34, v122
	v_fmac_f32_e32 v131, v35, v123
	v_fmac_f32_e32 v132, v36, v124
	v_fmac_f32_e32 v133, v37, v125
	v_fmac_f32_e32 v134, v38, v126
	v_fmac_f32_e32 v135, v39, v127
	v_cndmask_b32_e32 v112, v112, v128, vcc
	v_cndmask_b32_e32 v113, v113, v129, vcc
	v_cndmask_b32_e32 v114, v114, v130, vcc
	v_cndmask_b32_e32 v115, v115, v131, vcc
	v_cndmask_b32_e32 v116, v116, v132, vcc
	v_cndmask_b32_e32 v117, v117, v133, vcc
	v_cndmask_b32_e32 v118, v118, v134, vcc
	v_cndmask_b32_e32 v119, v119, v135, vcc
	v_mul_f32_e32 v112, 0x3e38aa3b, v112
	v_mul_f32_e32 v113, 0x3e38aa3b, v113
	v_mul_f32_e32 v114, 0x3e38aa3b, v114
	v_mul_f32_e32 v115, 0x3e38aa3b, v115
	v_mul_f32_e32 v116, 0x3e38aa3b, v116
	v_mul_f32_e32 v117, 0x3e38aa3b, v117
	v_mul_f32_e32 v118, 0x3e38aa3b, v118
	v_mul_f32_e32 v119, 0x3e38aa3b, v119
	v_cvt_pk_bf16_f32 v136, v112, v113
	v_cvt_pk_bf16_f32 v137, v114, v115
	v_cvt_pk_bf16_f32 v138, v116, v117
	v_cvt_pk_bf16_f32 v139, v118, v119
	global_store_dwordx4 v7, v[136:139], s[6:7]
	s_nop 1
	v_lshlrev_b32_e32 v112, 16, v92
	v_and_b32_e32 v113, 0xffff0000, v92
	v_lshlrev_b32_e32 v114, 16, v93
	v_and_b32_e32 v115, 0xffff0000, v93
	v_lshlrev_b32_e32 v116, 16, v94
	v_and_b32_e32 v117, 0xffff0000, v94
	v_lshlrev_b32_e32 v118, 16, v95
	v_and_b32_e32 v119, 0xffff0000, v95
	v_mul_f32_e32 v140, v112, v112
	v_mul_f32_e32 v141, v113, v113
	v_fmac_f32_e32 v140, v114, v114
	v_fmac_f32_e32 v141, v115, v115
	v_fmac_f32_e32 v140, v116, v116
	v_fmac_f32_e32 v141, v117, v117
	v_fmac_f32_e32 v140, v118, v118
	v_fmac_f32_e32 v141, v119, v119
	v_add_f32_e32 v140, v140, v141
	s_nop 1
	v_add_f32_dpp v140, v140, v140 quad_perm:[1,0,3,2] row_mask:0xf bank_mask:0xf bound_ctrl:1
	s_nop 1
	v_add_f32_dpp v140, v140, v140 quad_perm:[2,3,0,1] row_mask:0xf bank_mask:0xf bound_ctrl:1
	s_nop 1
	v_add_f32_dpp v140, v140, v140 row_half_mirror row_mask:0xf bank_mask:0xf bound_ctrl:1
	v_fma_f32 v141, v140, s10, v15
	v_rsq_f32_e32 v141, v141
	s_nop 0
	v_mul_f32_e32 v112, v112, v141
	v_mul_f32_e32 v113, v113, v141
	v_mul_f32_e32 v114, v114, v141
	v_mul_f32_e32 v115, v115, v141
	v_mul_f32_e32 v116, v116, v141
	v_mul_f32_e32 v117, v117, v141
	v_mul_f32_e32 v118, v118, v141
	v_mul_f32_e32 v119, v119, v141
	v_mul_f32_e32 v112, v112, v24
	v_mul_f32_e32 v113, v113, v25
	v_mul_f32_e32 v114, v114, v26
	v_mul_f32_e32 v115, v115, v27
	v_mul_f32_e32 v116, v116, v28
	v_mul_f32_e32 v117, v117, v29
	v_mul_f32_e32 v118, v118, v30
	v_mul_f32_e32 v119, v119, v31
	v_mov_b32_dpp v120, v112 quad_perm:[1,0,3,2] row_mask:0xf bank_mask:0xf
	v_mov_b32_dpp v121, v113 quad_perm:[1,0,3,2] row_mask:0xf bank_mask:0xf
	v_mov_b32_dpp v122, v114 quad_perm:[1,0,3,2] row_mask:0xf bank_mask:0xf
	v_mov_b32_dpp v123, v115 quad_perm:[1,0,3,2] row_mask:0xf bank_mask:0xf
	v_mov_b32_dpp v124, v116 quad_perm:[1,0,3,2] row_mask:0xf bank_mask:0xf
	v_mov_b32_dpp v125, v117 quad_perm:[1,0,3,2] row_mask:0xf bank_mask:0xf
	v_mov_b32_dpp v126, v118 quad_perm:[1,0,3,2] row_mask:0xf bank_mask:0xf
	v_mov_b32_dpp v127, v119 quad_perm:[1,0,3,2] row_mask:0xf bank_mask:0xf
	v_mul_f32_e32 v128, s28, v112
	v_mul_f32_e32 v129, s29, v113
	v_mul_f32_e32 v130, s30, v114
	v_mul_f32_e32 v131, s31, v115
	v_mul_f32_e32 v132, s34, v116
	v_mul_f32_e32 v133, s35, v117
	v_mul_f32_e32 v134, s36, v118
	v_mul_f32_e32 v135, s37, v119
	v_fmac_f32_e32 v128, v32, v120
	v_fmac_f32_e32 v129, v33, v121
	v_fmac_f32_e32 v130, v34, v122
	v_fmac_f32_e32 v131, v35, v123
	v_fmac_f32_e32 v132, v36, v124
	v_fmac_f32_e32 v133, v37, v125
	v_fmac_f32_e32 v134, v38, v126
	v_fmac_f32_e32 v135, v39, v127
	v_cndmask_b32_e32 v112, v112, v128, vcc
	v_cndmask_b32_e32 v113, v113, v129, vcc
	v_cndmask_b32_e32 v114, v114, v130, vcc
	v_cndmask_b32_e32 v115, v115, v131, vcc
	v_cndmask_b32_e32 v116, v116, v132, vcc
	v_cndmask_b32_e32 v117, v117, v133, vcc
	v_cndmask_b32_e32 v118, v118, v134, vcc
	v_cndmask_b32_e32 v119, v119, v135, vcc
	v_cvt_pk_bf16_f32 v136, v112, v113
	v_cvt_pk_bf16_f32 v137, v114, v115
	v_cvt_pk_bf16_f32 v138, v116, v117
	v_cvt_pk_bf16_f32 v139, v118, v119
	v_cndmask_b32_e64 v136, v136, v92, s[18:19]
	v_cndmask_b32_e64 v137, v137, v93, s[18:19]
	v_cndmask_b32_e64 v138, v138, v94, s[18:19]
	v_cndmask_b32_e64 v139, v139, v95, s[18:19]
	global_store_dwordx4 v8, v[136:139], s[12:13]
	s_add_u32 s6, s6, 0x200000
	s_addc_u32 s7, s7, 0
	s_add_u32 s12, s12, 0x80000
	s_addc_u32 s13, s13, 0
	s_waitcnt vmcnt(14)
	v_readlane_b32 s28, v11, 48
	v_readlane_b32 s38, v12, 48
	v_readlane_b32 s29, v11, 49
	v_readlane_b32 s39, v12, 49
	v_readlane_b32 s30, v11, 50
	v_readlane_b32 s40, v12, 50
	v_readlane_b32 s31, v11, 51
	v_readlane_b32 s41, v12, 51
	v_readlane_b32 s34, v11, 52
	v_readlane_b32 s42, v12, 52
	v_readlane_b32 s35, v11, 53
	v_readlane_b32 s43, v12, 53
	v_readlane_b32 s36, v11, 54
	v_readlane_b32 s44, v12, 54
	v_readlane_b32 s37, v11, 55
	v_readlane_b32 s45, v12, 55
	v_mul_f32_e32 v32, s38, v10
	v_mul_f32_e32 v33, s39, v10
	v_mul_f32_e32 v34, s40, v10
	v_mul_f32_e32 v35, s41, v10
	v_mul_f32_e32 v36, s42, v10
	v_mul_f32_e32 v37, s43, v10
	v_mul_f32_e32 v38, s44, v10
	v_mul_f32_e32 v39, s45, v10
	v_lshlrev_b32_e32 v112, 16, v96
	v_and_b32_e32 v113, 0xffff0000, v96
	v_lshlrev_b32_e32 v114, 16, v97
	v_and_b32_e32 v115, 0xffff0000, v97
	v_lshlrev_b32_e32 v116, 16, v98
	v_and_b32_e32 v117, 0xffff0000, v98
	v_lshlrev_b32_e32 v118, 16, v99
	v_and_b32_e32 v119, 0xffff0000, v99
	v_mul_f32_e32 v140, v112, v112
	v_mul_f32_e32 v141, v113, v113
	v_fmac_f32_e32 v140, v114, v114
	v_fmac_f32_e32 v141, v115, v115
	v_fmac_f32_e32 v140, v116, v116
	v_fmac_f32_e32 v141, v117, v117
	v_fmac_f32_e32 v140, v118, v118
	v_fmac_f32_e32 v141, v119, v119
	v_add_f32_e32 v140, v140, v141
	s_nop 1
	v_add_f32_dpp v140, v140, v140 quad_perm:[1,0,3,2] row_mask:0xf bank_mask:0xf bound_ctrl:1
	s_nop 1
	v_add_f32_dpp v140, v140, v140 quad_perm:[2,3,0,1] row_mask:0xf bank_mask:0xf bound_ctrl:1
	s_nop 1
	v_add_f32_dpp v140, v140, v140 row_half_mirror row_mask:0xf bank_mask:0xf bound_ctrl:1
	v_fma_f32 v141, v140, s10, v15
	v_rsq_f32_e32 v141, v141
	s_nop 0
	v_mul_f32_e32 v112, v112, v141
	v_mul_f32_e32 v113, v113, v141
	v_mul_f32_e32 v114, v114, v141
	v_mul_f32_e32 v115, v115, v141
	v_mul_f32_e32 v116, v116, v141
	v_mul_f32_e32 v117, v117, v141
	v_mul_f32_e32 v118, v118, v141
	v_mul_f32_e32 v119, v119, v141
	v_mul_f32_e32 v112, v112, v16
	v_mul_f32_e32 v113, v113, v17
	v_mul_f32_e32 v114, v114, v18
	v_mul_f32_e32 v115, v115, v19
	v_mul_f32_e32 v116, v116, v20
	v_mul_f32_e32 v117, v117, v21
	v_mul_f32_e32 v118, v118, v22
	v_mul_f32_e32 v119, v119, v23
	v_mov_b32_dpp v120, v112 quad_perm:[1,0,3,2] row_mask:0xf bank_mask:0xf
	v_mov_b32_dpp v121, v113 quad_perm:[1,0,3,2] row_mask:0xf bank_mask:0xf
	v_mov_b32_dpp v122, v114 quad_perm:[1,0,3,2] row_mask:0xf bank_mask:0xf
	v_mov_b32_dpp v123, v115 quad_perm:[1,0,3,2] row_mask:0xf bank_mask:0xf
	v_mov_b32_dpp v124, v116 quad_perm:[1,0,3,2] row_mask:0xf bank_mask:0xf
	v_mov_b32_dpp v125, v117 quad_perm:[1,0,3,2] row_mask:0xf bank_mask:0xf
	v_mov_b32_dpp v126, v118 quad_perm:[1,0,3,2] row_mask:0xf bank_mask:0xf
	v_mov_b32_dpp v127, v119 quad_perm:[1,0,3,2] row_mask:0xf bank_mask:0xf
	v_mul_f32_e32 v128, s28, v112
	v_mul_f32_e32 v129, s29, v113
	v_mul_f32_e32 v130, s30, v114
	v_mul_f32_e32 v131, s31, v115
	v_mul_f32_e32 v132, s34, v116
	v_mul_f32_e32 v133, s35, v117
	v_mul_f32_e32 v134, s36, v118
	v_mul_f32_e32 v135, s37, v119
	v_fmac_f32_e32 v128, v32, v120
	v_fmac_f32_e32 v129, v33, v121
	v_fmac_f32_e32 v130, v34, v122
	v_fmac_f32_e32 v131, v35, v123
	v_fmac_f32_e32 v132, v36, v124
	v_fmac_f32_e32 v133, v37, v125
	v_fmac_f32_e32 v134, v38, v126
	v_fmac_f32_e32 v135, v39, v127
	v_cndmask_b32_e32 v112, v112, v128, vcc
	v_cndmask_b32_e32 v113, v113, v129, vcc
	v_cndmask_b32_e32 v114, v114, v130, vcc
	v_cndmask_b32_e32 v115, v115, v131, vcc
	v_cndmask_b32_e32 v116, v116, v132, vcc
	v_cndmask_b32_e32 v117, v117, v133, vcc
	v_cndmask_b32_e32 v118, v118, v134, vcc
	v_cndmask_b32_e32 v119, v119, v135, vcc
	v_mul_f32_e32 v112, 0x3e38aa3b, v112
	v_mul_f32_e32 v113, 0x3e38aa3b, v113
	v_mul_f32_e32 v114, 0x3e38aa3b, v114
	v_mul_f32_e32 v115, 0x3e38aa3b, v115
	v_mul_f32_e32 v116, 0x3e38aa3b, v116
	v_mul_f32_e32 v117, 0x3e38aa3b, v117
	v_mul_f32_e32 v118, 0x3e38aa3b, v118
	v_mul_f32_e32 v119, 0x3e38aa3b, v119
	v_cvt_pk_bf16_f32 v136, v112, v113
	v_cvt_pk_bf16_f32 v137, v114, v115
	v_cvt_pk_bf16_f32 v138, v116, v117
	v_cvt_pk_bf16_f32 v139, v118, v119
	global_store_dwordx4 v7, v[136:139], s[6:7]
	s_nop 1
	v_lshlrev_b32_e32 v112, 16, v100
	v_and_b32_e32 v113, 0xffff0000, v100
	v_lshlrev_b32_e32 v114, 16, v101
	v_and_b32_e32 v115, 0xffff0000, v101
	v_lshlrev_b32_e32 v116, 16, v102
	v_and_b32_e32 v117, 0xffff0000, v102
	v_lshlrev_b32_e32 v118, 16, v103
	v_and_b32_e32 v119, 0xffff0000, v103
	v_mul_f32_e32 v140, v112, v112
	v_mul_f32_e32 v141, v113, v113
	v_fmac_f32_e32 v140, v114, v114
	v_fmac_f32_e32 v141, v115, v115
	v_fmac_f32_e32 v140, v116, v116
	v_fmac_f32_e32 v141, v117, v117
	v_fmac_f32_e32 v140, v118, v118
	v_fmac_f32_e32 v141, v119, v119
	v_add_f32_e32 v140, v140, v141
	s_nop 1
	v_add_f32_dpp v140, v140, v140 quad_perm:[1,0,3,2] row_mask:0xf bank_mask:0xf bound_ctrl:1
	s_nop 1
	v_add_f32_dpp v140, v140, v140 quad_perm:[2,3,0,1] row_mask:0xf bank_mask:0xf bound_ctrl:1
	s_nop 1
	v_add_f32_dpp v140, v140, v140 row_half_mirror row_mask:0xf bank_mask:0xf bound_ctrl:1
	v_fma_f32 v141, v140, s10, v15
	v_rsq_f32_e32 v141, v141
	s_nop 0
	v_mul_f32_e32 v112, v112, v141
	v_mul_f32_e32 v113, v113, v141
	v_mul_f32_e32 v114, v114, v141
	v_mul_f32_e32 v115, v115, v141
	v_mul_f32_e32 v116, v116, v141
	v_mul_f32_e32 v117, v117, v141
	v_mul_f32_e32 v118, v118, v141
	v_mul_f32_e32 v119, v119, v141
	v_mul_f32_e32 v112, v112, v24
	v_mul_f32_e32 v113, v113, v25
	v_mul_f32_e32 v114, v114, v26
	v_mul_f32_e32 v115, v115, v27
	v_mul_f32_e32 v116, v116, v28
	v_mul_f32_e32 v117, v117, v29
	v_mul_f32_e32 v118, v118, v30
	v_mul_f32_e32 v119, v119, v31
	v_mov_b32_dpp v120, v112 quad_perm:[1,0,3,2] row_mask:0xf bank_mask:0xf
	v_mov_b32_dpp v121, v113 quad_perm:[1,0,3,2] row_mask:0xf bank_mask:0xf
	v_mov_b32_dpp v122, v114 quad_perm:[1,0,3,2] row_mask:0xf bank_mask:0xf
	v_mov_b32_dpp v123, v115 quad_perm:[1,0,3,2] row_mask:0xf bank_mask:0xf
	v_mov_b32_dpp v124, v116 quad_perm:[1,0,3,2] row_mask:0xf bank_mask:0xf
	v_mov_b32_dpp v125, v117 quad_perm:[1,0,3,2] row_mask:0xf bank_mask:0xf
	v_mov_b32_dpp v126, v118 quad_perm:[1,0,3,2] row_mask:0xf bank_mask:0xf
	v_mov_b32_dpp v127, v119 quad_perm:[1,0,3,2] row_mask:0xf bank_mask:0xf
	v_mul_f32_e32 v128, s28, v112
	v_mul_f32_e32 v129, s29, v113
	v_mul_f32_e32 v130, s30, v114
	v_mul_f32_e32 v131, s31, v115
	v_mul_f32_e32 v132, s34, v116
	v_mul_f32_e32 v133, s35, v117
	v_mul_f32_e32 v134, s36, v118
	v_mul_f32_e32 v135, s37, v119
	v_fmac_f32_e32 v128, v32, v120
	v_fmac_f32_e32 v129, v33, v121
	v_fmac_f32_e32 v130, v34, v122
	v_fmac_f32_e32 v131, v35, v123
	v_fmac_f32_e32 v132, v36, v124
	v_fmac_f32_e32 v133, v37, v125
	v_fmac_f32_e32 v134, v38, v126
	v_fmac_f32_e32 v135, v39, v127
	v_cndmask_b32_e32 v112, v112, v128, vcc
	v_cndmask_b32_e32 v113, v113, v129, vcc
	v_cndmask_b32_e32 v114, v114, v130, vcc
	v_cndmask_b32_e32 v115, v115, v131, vcc
	v_cndmask_b32_e32 v116, v116, v132, vcc
	v_cndmask_b32_e32 v117, v117, v133, vcc
	v_cndmask_b32_e32 v118, v118, v134, vcc
	v_cndmask_b32_e32 v119, v119, v135, vcc
	v_cvt_pk_bf16_f32 v136, v112, v113
	v_cvt_pk_bf16_f32 v137, v114, v115
	v_cvt_pk_bf16_f32 v138, v116, v117
	v_cvt_pk_bf16_f32 v139, v118, v119
	v_cndmask_b32_e64 v136, v136, v100, s[18:19]
	v_cndmask_b32_e64 v137, v137, v101, s[18:19]
	v_cndmask_b32_e64 v138, v138, v102, s[18:19]
	v_cndmask_b32_e64 v139, v139, v103, s[18:19]
	global_store_dwordx4 v8, v[136:139], s[12:13]
	s_add_u32 s6, s6, 0x200000
	s_addc_u32 s7, s7, 0
	s_add_u32 s12, s12, 0x80000
	s_addc_u32 s13, s13, 0
	s_waitcnt vmcnt(14)
	v_readlane_b32 s28, v11, 56
	v_readlane_b32 s38, v12, 56
	v_readlane_b32 s29, v11, 57
	v_readlane_b32 s39, v12, 57
	v_readlane_b32 s30, v11, 58
	v_readlane_b32 s40, v12, 58
	v_readlane_b32 s31, v11, 59
	v_readlane_b32 s41, v12, 59
	v_readlane_b32 s34, v11, 60
	v_readlane_b32 s42, v12, 60
	v_readlane_b32 s35, v11, 61
	v_readlane_b32 s43, v12, 61
	v_readlane_b32 s36, v11, 62
	v_readlane_b32 s44, v12, 62
	v_readlane_b32 s37, v11, 63
	v_readlane_b32 s45, v12, 63
	v_mul_f32_e32 v32, s38, v10
	v_mul_f32_e32 v33, s39, v10
	v_mul_f32_e32 v34, s40, v10
	v_mul_f32_e32 v35, s41, v10
	v_mul_f32_e32 v36, s42, v10
	v_mul_f32_e32 v37, s43, v10
	v_mul_f32_e32 v38, s44, v10
	v_mul_f32_e32 v39, s45, v10
	v_lshlrev_b32_e32 v112, 16, v104
	v_and_b32_e32 v113, 0xffff0000, v104
	v_lshlrev_b32_e32 v114, 16, v105
	v_and_b32_e32 v115, 0xffff0000, v105
	v_lshlrev_b32_e32 v116, 16, v106
	v_and_b32_e32 v117, 0xffff0000, v106
	v_lshlrev_b32_e32 v118, 16, v107
	v_and_b32_e32 v119, 0xffff0000, v107
	v_mul_f32_e32 v140, v112, v112
	v_mul_f32_e32 v141, v113, v113
	v_fmac_f32_e32 v140, v114, v114
	v_fmac_f32_e32 v141, v115, v115
	v_fmac_f32_e32 v140, v116, v116
	v_fmac_f32_e32 v141, v117, v117
	v_fmac_f32_e32 v140, v118, v118
	v_fmac_f32_e32 v141, v119, v119
	v_add_f32_e32 v140, v140, v141
	s_nop 1
	v_add_f32_dpp v140, v140, v140 quad_perm:[1,0,3,2] row_mask:0xf bank_mask:0xf bound_ctrl:1
	s_nop 1
	v_add_f32_dpp v140, v140, v140 quad_perm:[2,3,0,1] row_mask:0xf bank_mask:0xf bound_ctrl:1
	s_nop 1
	v_add_f32_dpp v140, v140, v140 row_half_mirror row_mask:0xf bank_mask:0xf bound_ctrl:1
	v_fma_f32 v141, v140, s10, v15
	v_rsq_f32_e32 v141, v141
	s_nop 0
	v_mul_f32_e32 v112, v112, v141
	v_mul_f32_e32 v113, v113, v141
	v_mul_f32_e32 v114, v114, v141
	v_mul_f32_e32 v115, v115, v141
	v_mul_f32_e32 v116, v116, v141
	v_mul_f32_e32 v117, v117, v141
	v_mul_f32_e32 v118, v118, v141
	v_mul_f32_e32 v119, v119, v141
	v_mul_f32_e32 v112, v112, v16
	v_mul_f32_e32 v113, v113, v17
	v_mul_f32_e32 v114, v114, v18
	v_mul_f32_e32 v115, v115, v19
	v_mul_f32_e32 v116, v116, v20
	v_mul_f32_e32 v117, v117, v21
	v_mul_f32_e32 v118, v118, v22
	v_mul_f32_e32 v119, v119, v23
	v_mov_b32_dpp v120, v112 quad_perm:[1,0,3,2] row_mask:0xf bank_mask:0xf
	v_mov_b32_dpp v121, v113 quad_perm:[1,0,3,2] row_mask:0xf bank_mask:0xf
	v_mov_b32_dpp v122, v114 quad_perm:[1,0,3,2] row_mask:0xf bank_mask:0xf
	v_mov_b32_dpp v123, v115 quad_perm:[1,0,3,2] row_mask:0xf bank_mask:0xf
	v_mov_b32_dpp v124, v116 quad_perm:[1,0,3,2] row_mask:0xf bank_mask:0xf
	v_mov_b32_dpp v125, v117 quad_perm:[1,0,3,2] row_mask:0xf bank_mask:0xf
	v_mov_b32_dpp v126, v118 quad_perm:[1,0,3,2] row_mask:0xf bank_mask:0xf
	v_mov_b32_dpp v127, v119 quad_perm:[1,0,3,2] row_mask:0xf bank_mask:0xf
	v_mul_f32_e32 v128, s28, v112
	v_mul_f32_e32 v129, s29, v113
	v_mul_f32_e32 v130, s30, v114
	v_mul_f32_e32 v131, s31, v115
	v_mul_f32_e32 v132, s34, v116
	v_mul_f32_e32 v133, s35, v117
	v_mul_f32_e32 v134, s36, v118
	v_mul_f32_e32 v135, s37, v119
	v_fmac_f32_e32 v128, v32, v120
	v_fmac_f32_e32 v129, v33, v121
	v_fmac_f32_e32 v130, v34, v122
	v_fmac_f32_e32 v131, v35, v123
	v_fmac_f32_e32 v132, v36, v124
	v_fmac_f32_e32 v133, v37, v125
	v_fmac_f32_e32 v134, v38, v126
	v_fmac_f32_e32 v135, v39, v127
	v_cndmask_b32_e32 v112, v112, v128, vcc
	v_cndmask_b32_e32 v113, v113, v129, vcc
	v_cndmask_b32_e32 v114, v114, v130, vcc
	v_cndmask_b32_e32 v115, v115, v131, vcc
	v_cndmask_b32_e32 v116, v116, v132, vcc
	v_cndmask_b32_e32 v117, v117, v133, vcc
	v_cndmask_b32_e32 v118, v118, v134, vcc
	v_cndmask_b32_e32 v119, v119, v135, vcc
	v_mul_f32_e32 v112, 0x3e38aa3b, v112
	v_mul_f32_e32 v113, 0x3e38aa3b, v113
	v_mul_f32_e32 v114, 0x3e38aa3b, v114
	v_mul_f32_e32 v115, 0x3e38aa3b, v115
	v_mul_f32_e32 v116, 0x3e38aa3b, v116
	v_mul_f32_e32 v117, 0x3e38aa3b, v117
	v_mul_f32_e32 v118, 0x3e38aa3b, v118
	v_mul_f32_e32 v119, 0x3e38aa3b, v119
	v_cvt_pk_bf16_f32 v136, v112, v113
	v_cvt_pk_bf16_f32 v137, v114, v115
	v_cvt_pk_bf16_f32 v138, v116, v117
	v_cvt_pk_bf16_f32 v139, v118, v119
	global_store_dwordx4 v7, v[136:139], s[6:7]
	s_nop 1
	v_lshlrev_b32_e32 v112, 16, v108
	v_and_b32_e32 v113, 0xffff0000, v108
	v_lshlrev_b32_e32 v114, 16, v109
	v_and_b32_e32 v115, 0xffff0000, v109
	v_lshlrev_b32_e32 v116, 16, v110
	v_and_b32_e32 v117, 0xffff0000, v110
	v_lshlrev_b32_e32 v118, 16, v111
	v_and_b32_e32 v119, 0xffff0000, v111
	v_mul_f32_e32 v140, v112, v112
	v_mul_f32_e32 v141, v113, v113
	v_fmac_f32_e32 v140, v114, v114
	v_fmac_f32_e32 v141, v115, v115
	v_fmac_f32_e32 v140, v116, v116
	v_fmac_f32_e32 v141, v117, v117
	v_fmac_f32_e32 v140, v118, v118
	v_fmac_f32_e32 v141, v119, v119
	v_add_f32_e32 v140, v140, v141
	s_nop 1
	v_add_f32_dpp v140, v140, v140 quad_perm:[1,0,3,2] row_mask:0xf bank_mask:0xf bound_ctrl:1
	s_nop 1
	v_add_f32_dpp v140, v140, v140 quad_perm:[2,3,0,1] row_mask:0xf bank_mask:0xf bound_ctrl:1
	s_nop 1
	v_add_f32_dpp v140, v140, v140 row_half_mirror row_mask:0xf bank_mask:0xf bound_ctrl:1
	v_fma_f32 v141, v140, s10, v15
	v_rsq_f32_e32 v141, v141
	s_nop 0
	v_mul_f32_e32 v112, v112, v141
	v_mul_f32_e32 v113, v113, v141
	v_mul_f32_e32 v114, v114, v141
	v_mul_f32_e32 v115, v115, v141
	v_mul_f32_e32 v116, v116, v141
	v_mul_f32_e32 v117, v117, v141
	v_mul_f32_e32 v118, v118, v141
	v_mul_f32_e32 v119, v119, v141
	v_mul_f32_e32 v112, v112, v24
	v_mul_f32_e32 v113, v113, v25
	v_mul_f32_e32 v114, v114, v26
	v_mul_f32_e32 v115, v115, v27
	v_mul_f32_e32 v116, v116, v28
	v_mul_f32_e32 v117, v117, v29
	v_mul_f32_e32 v118, v118, v30
	v_mul_f32_e32 v119, v119, v31
	v_mov_b32_dpp v120, v112 quad_perm:[1,0,3,2] row_mask:0xf bank_mask:0xf
	v_mov_b32_dpp v121, v113 quad_perm:[1,0,3,2] row_mask:0xf bank_mask:0xf
	v_mov_b32_dpp v122, v114 quad_perm:[1,0,3,2] row_mask:0xf bank_mask:0xf
	v_mov_b32_dpp v123, v115 quad_perm:[1,0,3,2] row_mask:0xf bank_mask:0xf
	v_mov_b32_dpp v124, v116 quad_perm:[1,0,3,2] row_mask:0xf bank_mask:0xf
	v_mov_b32_dpp v125, v117 quad_perm:[1,0,3,2] row_mask:0xf bank_mask:0xf
	v_mov_b32_dpp v126, v118 quad_perm:[1,0,3,2] row_mask:0xf bank_mask:0xf
	v_mov_b32_dpp v127, v119 quad_perm:[1,0,3,2] row_mask:0xf bank_mask:0xf
	v_mul_f32_e32 v128, s28, v112
	v_mul_f32_e32 v129, s29, v113
	v_mul_f32_e32 v130, s30, v114
	v_mul_f32_e32 v131, s31, v115
	v_mul_f32_e32 v132, s34, v116
	v_mul_f32_e32 v133, s35, v117
	v_mul_f32_e32 v134, s36, v118
	v_mul_f32_e32 v135, s37, v119
	v_fmac_f32_e32 v128, v32, v120
	v_fmac_f32_e32 v129, v33, v121
	v_fmac_f32_e32 v130, v34, v122
	v_fmac_f32_e32 v131, v35, v123
	v_fmac_f32_e32 v132, v36, v124
	v_fmac_f32_e32 v133, v37, v125
	v_fmac_f32_e32 v134, v38, v126
	v_fmac_f32_e32 v135, v39, v127
	v_cndmask_b32_e32 v112, v112, v128, vcc
	v_cndmask_b32_e32 v113, v113, v129, vcc
	v_cndmask_b32_e32 v114, v114, v130, vcc
	v_cndmask_b32_e32 v115, v115, v131, vcc
	v_cndmask_b32_e32 v116, v116, v132, vcc
	v_cndmask_b32_e32 v117, v117, v133, vcc
	v_cndmask_b32_e32 v118, v118, v134, vcc
	v_cndmask_b32_e32 v119, v119, v135, vcc
	v_cvt_pk_bf16_f32 v136, v112, v113
	v_cvt_pk_bf16_f32 v137, v114, v115
	v_cvt_pk_bf16_f32 v138, v116, v117
	v_cvt_pk_bf16_f32 v139, v118, v119
	v_cndmask_b32_e64 v136, v136, v108, s[18:19]
	v_cndmask_b32_e64 v137, v137, v109, s[18:19]
	v_cndmask_b32_e64 v138, v138, v110, s[18:19]
	v_cndmask_b32_e64 v139, v139, v111, s[18:19]
	global_store_dwordx4 v8, v[136:139], s[12:13]
	s_add_u32 s6, s6, 0x200000
	s_addc_u32 s7, s7, 0
	s_add_u32 s12, s12, 0x80000
	s_addc_u32 s13, s13, 0
	s_branch .LBB0_278
	s_nop 0
	s_nop 0
	s_nop 0
	s_nop 0
	s_nop 0
	s_nop 0
	s_nop 0
	s_nop 0
	s_nop 0
	s_nop 0
	s_nop 0
	s_nop 0
	s_nop 0
	s_nop 0
	s_nop 0
	s_nop 0
	s_nop 0
	s_nop 0
	s_nop 0
	s_nop 0
	s_nop 0
	s_nop 0
	s_nop 0
	s_nop 0
	s_nop 0
	s_nop 0
	s_nop 0
	s_nop 0
	s_nop 0
	s_nop 0
	s_nop 0
	s_nop 0
	s_nop 0
	s_nop 0
	s_nop 0
	s_nop 0
	s_nop 0
	s_nop 0
	s_nop 0
	s_nop 0
	s_nop 0
	s_nop 0
	s_nop 0
	s_nop 0
	s_nop 0
	s_nop 0
	s_nop 0
	s_nop 0
	s_nop 0
	s_nop 0
	s_nop 0
	s_nop 0
	s_nop 0
	s_nop 0
	s_nop 0
	s_nop 0
	s_nop 0
	s_nop 0
	s_nop 0
	s_nop 0
	s_nop 0
	s_nop 0
	s_nop 0
	s_nop 0
	s_nop 0
	s_nop 0
	s_nop 0
	s_nop 0
	s_nop 0
	s_nop 0
	s_nop 0
	s_nop 0
	s_nop 0
	s_nop 0
	s_nop 0
	s_nop 0
	s_nop 0
	s_nop 0
	s_nop 0
	s_nop 0
	s_nop 0
	s_nop 0
	s_nop 0
	s_nop 0
	s_nop 0
	s_nop 0
	s_nop 0
	s_nop 0
	s_nop 0
	s_nop 0
	s_nop 0
	s_nop 0
	s_nop 0
	s_nop 0
	s_nop 0
	s_nop 0
	s_nop 0
	s_nop 0
	s_nop 0
	s_nop 0
	s_nop 0
	s_nop 0
	s_nop 0
	s_nop 0
	s_nop 0
	s_nop 0
	s_nop 0
	s_nop 0
	s_nop 0
	s_nop 0
	s_nop 0
	s_nop 0
	s_nop 0
	s_nop 0
	s_nop 0
	s_nop 0
	s_nop 0
	s_nop 0
	s_nop 0
	s_nop 0
	s_nop 0
	s_nop 0
	s_nop 0
	s_nop 0
	s_nop 0
	s_nop 0
	s_nop 0
	s_nop 0
	s_nop 0
	s_nop 0
	s_nop 0
	s_nop 0
	s_nop 0
	s_nop 0
	s_nop 0
	s_nop 0
	s_nop 0
	s_nop 0
	s_nop 0
	s_nop 0
	s_nop 0
	s_nop 0
	s_nop 0
	s_nop 0
	s_nop 0
	s_nop 0
	s_nop 0
	s_nop 0
	s_nop 0
	s_nop 0
	s_nop 0
	s_nop 0
	s_nop 0
	s_nop 0
	s_nop 0
	s_nop 0
	s_nop 0
	s_nop 0
	s_nop 0
	s_nop 0
	s_nop 0
	s_nop 0
	s_nop 0
	s_nop 0
	s_nop 0
	s_nop 0
	s_nop 0
	s_nop 0
	s_nop 0
	s_nop 0
	s_nop 0
	s_nop 0
	s_nop 0
	s_nop 0
	s_nop 0
	s_nop 0
	s_nop 0
	s_nop 0
	s_nop 0
	s_nop 0
	s_nop 0
	s_nop 0
	s_nop 0
	s_nop 0
	s_nop 0
	s_nop 0
	s_nop 0
	s_nop 0
	s_nop 0
	s_nop 0
	s_nop 0
	s_nop 0
	s_nop 0
	s_nop 0
	s_nop 0
	s_nop 0
	s_nop 0
	s_nop 0
	s_nop 0
	s_nop 0
	s_nop 0
	s_nop 0
	s_nop 0
	s_nop 0
	s_nop 0
	s_nop 0
	s_nop 0
	s_nop 0
	s_nop 0
	s_nop 0
	s_nop 0
	s_nop 0
	s_nop 0
	s_nop 0
	s_nop 0
	s_nop 0
	s_nop 0
	s_nop 0
	s_nop 0
	s_nop 0
	s_nop 0
	s_nop 0
	s_nop 0
	s_nop 0
	s_nop 0
	s_nop 0
	s_nop 0
	s_nop 0
	s_nop 0
	s_nop 0
	s_nop 0
	s_nop 0
	s_nop 0
	s_nop 0
	s_nop 0
	s_nop 0
	s_nop 0
	s_nop 0
	s_nop 0
	s_nop 0
	s_nop 0
	s_nop 0
	s_nop 0
	s_nop 0
	s_nop 0
	s_nop 0
	s_nop 0
	s_nop 0
	s_nop 0
	s_nop 0
	s_nop 0
	s_nop 0
	s_nop 0
	s_nop 0
	s_nop 0
	s_nop 0
	s_nop 0
	s_nop 0
	s_nop 0
	s_nop 0
	s_nop 0
	s_nop 0
	s_nop 0
	s_nop 0
	s_nop 0
	s_nop 0
	s_nop 0
	s_nop 0
	s_nop 0
	s_nop 0
	s_nop 0
	s_nop 0
	s_nop 0
	s_nop 0
	s_nop 0
	s_nop 0
	s_nop 0
	s_nop 0
	s_nop 0
	s_nop 0
	s_nop 0
	s_nop 0
	s_nop 0
	s_nop 0
	s_nop 0
	s_nop 0
	s_nop 0
	s_nop 0
	s_nop 0
	s_nop 0
	s_nop 0
	s_nop 0
	s_nop 0
	s_nop 0
	s_nop 0
	s_nop 0
	s_nop 0
	s_nop 0
	s_nop 0
	s_nop 0
	s_nop 0
	s_nop 0
	s_nop 0
	s_nop 0
	s_nop 0
	s_nop 0
	s_nop 0
	s_nop 0
	s_nop 0
	s_nop 0

.LBB0_574:
	ds_read_b128 v[128:131], v161
	ds_read_b128 v[132:135], v161 offset:1024
	ds_read_b128 v[136:139], v161 offset:2048
	ds_read_b128 v[140:143], v161 offset:3072
	ds_read_b128 v[164:167], v162
	ds_read_b128 v[168:171], v162 offset:1024
	ds_read_b128 v[172:175], v162 offset:2048
	ds_read_b128 v[176:179], v162 offset:3072
	s_add_u32 s38, s36, 0xfffc0080
	s_addc_u32 s39, s37, -1
	s_cmp_eq_u32 s63, 12
	s_cselect_b32 s41, s21, s39
	s_cselect_b32 s40, s23, s38
	s_cselect_b32 s39, s59, s62
	s_cselect_b32 s38, s60, s61
	s_add_i32 m0, s35, 0xc000
	ds_read_b128 v[180:183], v163
	ds_read_b128 v[184:187], v163 offset:1024
	ds_read_b128 v[188:191], v163 offset:2048
	ds_read_b128 v[192:195], v163 offset:3072
	ds_read_b128 v[196:199], v163 offset:4096
	ds_read_b128 v[200:203], v163 offset:5120
	ds_read_b128 v[204:207], v163 offset:6144
	ds_read_b128 v[208:211], v163 offset:7168
	global_load_lds_dwordx4 v150, s[36:37]
	s_add_i32 m0, s35, 0xe000
	s_nop 0
	global_load_lds_dwordx4 v148, s[36:37]
	s_waitcnt vmcnt(8)
	s_waitcnt lgkmcnt(0)
	s_barrier
	s_setprio 1
	s_waitcnt lgkmcnt(0)
	v_mfma_f32_16x16x32_bf16 v[124:127], v[128:131], v[180:183], v[124:127]
	v_mfma_f32_16x16x32_bf16 v[120:123], v[136:139], v[180:183], v[120:123]
	v_mfma_f32_16x16x32_bf16 v[112:115], v[128:131], v[188:191], v[112:115]
	v_mfma_f32_16x16x32_bf16 v[108:111], v[136:139], v[188:191], v[108:111]
	v_mfma_f32_16x16x32_bf16 v[96:99], v[128:131], v[196:199], v[96:99]
	v_mfma_f32_16x16x32_bf16 v[92:95], v[136:139], v[196:199], v[92:95]
	v_mfma_f32_16x16x32_bf16 v[80:83], v[128:131], v[204:207], v[80:83]
	v_mfma_f32_16x16x32_bf16 v[76:79], v[136:139], v[204:207], v[76:79]
	v_mfma_f32_16x16x32_bf16 v[124:127], v[132:135], v[184:187], v[124:127]
	v_mfma_f32_16x16x32_bf16 v[120:123], v[140:143], v[184:187], v[120:123]
	v_mfma_f32_16x16x32_bf16 v[112:115], v[132:135], v[192:195], v[112:115]
	v_mfma_f32_16x16x32_bf16 v[108:111], v[140:143], v[192:195], v[108:111]
	v_mfma_f32_16x16x32_bf16 v[96:99], v[132:135], v[200:203], v[96:99]
	v_mfma_f32_16x16x32_bf16 v[92:95], v[140:143], v[200:203], v[92:95]
	v_mfma_f32_16x16x32_bf16 v[80:83], v[132:135], v[208:211], v[80:83]
	v_mfma_f32_16x16x32_bf16 v[76:79], v[140:143], v[208:211], v[76:79]
	s_setprio 0
	s_setprio 1
	v_mfma_f32_16x16x32_bf16 v[116:119], v[164:167], v[180:183], v[116:119]
	v_mfma_f32_16x16x32_bf16 v[104:107], v[172:175], v[180:183], v[104:107]
	v_mfma_f32_16x16x32_bf16 v[100:103], v[164:167], v[188:191], v[100:103]
	v_mfma_f32_16x16x32_bf16 v[88:91], v[172:175], v[188:191], v[88:91]
	v_mfma_f32_16x16x32_bf16 v[84:87], v[164:167], v[196:199], v[84:87]
	v_mfma_f32_16x16x32_bf16 v[72:75], v[172:175], v[196:199], v[72:75]
	v_mfma_f32_16x16x32_bf16 v[68:71], v[164:167], v[204:207], v[68:71]
	v_mfma_f32_16x16x32_bf16 v[64:67], v[172:175], v[204:207], v[64:67]
	v_mfma_f32_16x16x32_bf16 v[116:119], v[168:171], v[184:187], v[116:119]
	v_mfma_f32_16x16x32_bf16 v[104:107], v[176:179], v[184:187], v[104:107]
	v_mfma_f32_16x16x32_bf16 v[100:103], v[168:171], v[192:195], v[100:103]
	v_mfma_f32_16x16x32_bf16 v[88:91], v[176:179], v[192:195], v[88:91]
	v_mfma_f32_16x16x32_bf16 v[84:87], v[168:171], v[200:203], v[84:87]
	v_mfma_f32_16x16x32_bf16 v[72:75], v[176:179], v[200:203], v[72:75]
	v_mfma_f32_16x16x32_bf16 v[68:71], v[168:171], v[208:211], v[68:71]
	v_mfma_f32_16x16x32_bf16 v[64:67], v[176:179], v[208:211], v[64:67]
	s_setprio 0
	s_barrier
	s_add_i32 s64, s56, s70
	s_add_u32 s98, s38, s6
	s_addc_u32 s99, s39, s7
	s_add_u32 s100, s40, s6
	s_addc_u32 s101, s41, s7
	s_mov_b32 m0, s64
	ds_read_b128 v[180:183], v163 offset:16384
	ds_read_b128 v[184:187], v163 offset:17408
	ds_read_b128 v[188:191], v163 offset:18432
	ds_read_b128 v[192:195], v163 offset:19456
	ds_read_b128 v[196:199], v163 offset:20480
	ds_read_b128 v[200:203], v163 offset:21504
	ds_read_b128 v[204:207], v163 offset:22528
	ds_read_b128 v[208:211], v163 offset:23552
	global_load_lds_dwordx4 v144, s[38:39]
	s_add_i32 m0, s64, 0x2000
	s_add_u32 s64, s38, 0x40000
	s_addc_u32 s65, s39, 0
	s_add_i32 s66, s57, s70
	global_load_lds_dwordx4 v146, s[38:39]
	s_mov_b32 m0, s66
	s_nop 0
	global_load_lds_dwordx4 v144, s[64:65]
	s_add_i32 m0, s66, 0x2000
	s_nop 0
	global_load_lds_dwordx4 v146, s[64:65]
	s_mov_b32 m0, s35
	s_nop 0
	global_load_lds_dwordx4 v144, s[40:41]
	s_mov_b32 m0, s46
	s_nop 0
	global_load_lds_dwordx4 v146, s[40:41]
	s_waitcnt vmcnt(8)
	s_waitcnt lgkmcnt(0)
	s_barrier
	s_setprio 1
	s_waitcnt lgkmcnt(0)
	v_mfma_f32_16x16x32_bf16 v[60:63], v[128:131], v[180:183], v[60:63]
	v_mfma_f32_16x16x32_bf16 v[56:59], v[136:139], v[180:183], v[56:59]
	v_mfma_f32_16x16x32_bf16 v[48:51], v[128:131], v[188:191], v[48:51]
	v_mfma_f32_16x16x32_bf16 v[44:47], v[136:139], v[188:191], v[44:47]
	v_mfma_f32_16x16x32_bf16 v[32:35], v[128:131], v[196:199], v[32:35]
	v_mfma_f32_16x16x32_bf16 v[28:31], v[136:139], v[196:199], v[28:31]
	v_mfma_f32_16x16x32_bf16 v[16:19], v[128:131], v[204:207], v[16:19]
	v_mfma_f32_16x16x32_bf16 v[12:15], v[136:139], v[204:207], v[12:15]
	v_mfma_f32_16x16x32_bf16 v[60:63], v[132:135], v[184:187], v[60:63]
	v_mfma_f32_16x16x32_bf16 v[56:59], v[140:143], v[184:187], v[56:59]
	v_mfma_f32_16x16x32_bf16 v[48:51], v[132:135], v[192:195], v[48:51]
	v_mfma_f32_16x16x32_bf16 v[44:47], v[140:143], v[192:195], v[44:47]
	v_mfma_f32_16x16x32_bf16 v[32:35], v[132:135], v[200:203], v[32:35]
	v_mfma_f32_16x16x32_bf16 v[28:31], v[140:143], v[200:203], v[28:31]
	v_mfma_f32_16x16x32_bf16 v[16:19], v[132:135], v[208:211], v[16:19]
	v_mfma_f32_16x16x32_bf16 v[12:15], v[140:143], v[208:211], v[12:15]
	s_setprio 0
	s_setprio 1
	v_mfma_f32_16x16x32_bf16 v[52:55], v[164:167], v[180:183], v[52:55]
	v_mfma_f32_16x16x32_bf16 v[40:43], v[172:175], v[180:183], v[40:43]
	v_mfma_f32_16x16x32_bf16 v[36:39], v[164:167], v[188:191], v[36:39]
	v_mfma_f32_16x16x32_bf16 v[24:27], v[172:175], v[188:191], v[24:27]
	v_mfma_f32_16x16x32_bf16 v[20:23], v[164:167], v[196:199], v[20:23]
	v_mfma_f32_16x16x32_bf16 v[8:11], v[172:175], v[196:199], v[8:11]
	v_mfma_f32_16x16x32_bf16 v[4:7], v[164:167], v[204:207], v[4:7]
	v_mfma_f32_16x16x32_bf16 v[0:3], v[172:175], v[204:207], v[0:3]
	v_mfma_f32_16x16x32_bf16 v[52:55], v[168:171], v[184:187], v[52:55]
	v_mfma_f32_16x16x32_bf16 v[40:43], v[176:179], v[184:187], v[40:43]
	v_mfma_f32_16x16x32_bf16 v[36:39], v[168:171], v[192:195], v[36:39]
	v_mfma_f32_16x16x32_bf16 v[24:27], v[176:179], v[192:195], v[24:27]
	v_mfma_f32_16x16x32_bf16 v[20:23], v[168:171], v[200:203], v[20:23]
	v_mfma_f32_16x16x32_bf16 v[8:11], v[176:179], v[200:203], v[8:11]
	v_mfma_f32_16x16x32_bf16 v[4:7], v[168:171], v[208:211], v[4:7]
	v_mfma_f32_16x16x32_bf16 v[0:3], v[176:179], v[208:211], v[0:3]
	s_setprio 0
	s_barrier
	s_add_i32 s64, 0, 0x18000
	s_add_i32 s65, 0, 0x1c000
	v_add_u32_e32 v140, s64, v159
	v_add_u32_e32 v176, s65, v159
	ds_read_b128 v[128:131], v140
	ds_read_b128 v[132:135], v140 offset:1024
	ds_read_b128 v[136:139], v140 offset:2048
	ds_read_b128 v[140:143], v140 offset:3072
	ds_read_b128 v[164:167], v176
	ds_read_b128 v[168:171], v176 offset:1024
	ds_read_b128 v[172:175], v176 offset:2048
	ds_read_b128 v[176:179], v176 offset:3072
	s_add_u32 s40, s40, 0x40000
	s_addc_u32 s41, s41, 0
	s_mov_b32 m0, s47
	ds_read_b128 v[180:183], v163 offset:32768
	ds_read_b128 v[184:187], v163 offset:33792
	ds_read_b128 v[188:191], v163 offset:34816
	ds_read_b128 v[192:195], v163 offset:35840
	ds_read_b128 v[196:199], v163 offset:36864
	ds_read_b128 v[200:203], v163 offset:37888
	ds_read_b128 v[204:207], v163 offset:38912
	ds_read_b128 v[208:211], v163 offset:39936
	global_load_lds_dwordx4 v144, s[40:41]
	s_mov_b32 m0, s48
	s_nop 0
	global_load_lds_dwordx4 v146, s[40:41]
	s_waitcnt vmcnt(8)
	s_waitcnt lgkmcnt(0)
	s_barrier
	s_setprio 1
	s_waitcnt lgkmcnt(0)
	v_mfma_f32_16x16x32_bf16 v[124:127], v[128:131], v[180:183], v[124:127]
	v_mfma_f32_16x16x32_bf16 v[120:123], v[136:139], v[180:183], v[120:123]
	v_mfma_f32_16x16x32_bf16 v[112:115], v[128:131], v[188:191], v[112:115]
	v_mfma_f32_16x16x32_bf16 v[108:111], v[136:139], v[188:191], v[108:111]
	v_mfma_f32_16x16x32_bf16 v[96:99], v[128:131], v[196:199], v[96:99]
	v_mfma_f32_16x16x32_bf16 v[92:95], v[136:139], v[196:199], v[92:95]
	v_mfma_f32_16x16x32_bf16 v[80:83], v[128:131], v[204:207], v[80:83]
	v_mfma_f32_16x16x32_bf16 v[76:79], v[136:139], v[204:207], v[76:79]
	v_mfma_f32_16x16x32_bf16 v[124:127], v[132:135], v[184:187], v[124:127]
	v_mfma_f32_16x16x32_bf16 v[120:123], v[140:143], v[184:187], v[120:123]
	v_mfma_f32_16x16x32_bf16 v[112:115], v[132:135], v[192:195], v[112:115]
	v_mfma_f32_16x16x32_bf16 v[108:111], v[140:143], v[192:195], v[108:111]
	v_mfma_f32_16x16x32_bf16 v[96:99], v[132:135], v[200:203], v[96:99]
	v_mfma_f32_16x16x32_bf16 v[92:95], v[140:143], v[200:203], v[92:95]
	v_mfma_f32_16x16x32_bf16 v[80:83], v[132:135], v[208:211], v[80:83]
	v_mfma_f32_16x16x32_bf16 v[76:79], v[140:143], v[208:211], v[76:79]
	s_setprio 0
	s_setprio 1
	v_mfma_f32_16x16x32_bf16 v[116:119], v[164:167], v[180:183], v[116:119]
	v_mfma_f32_16x16x32_bf16 v[104:107], v[172:175], v[180:183], v[104:107]
	v_mfma_f32_16x16x32_bf16 v[100:103], v[164:167], v[188:191], v[100:103]
	v_mfma_f32_16x16x32_bf16 v[88:91], v[172:175], v[188:191], v[88:91]
	v_mfma_f32_16x16x32_bf16 v[84:87], v[164:167], v[196:199], v[84:87]
	v_mfma_f32_16x16x32_bf16 v[72:75], v[172:175], v[196:199], v[72:75]
	v_mfma_f32_16x16x32_bf16 v[68:71], v[164:167], v[204:207], v[68:71]
	v_mfma_f32_16x16x32_bf16 v[64:67], v[172:175], v[204:207], v[64:67]
	v_mfma_f32_16x16x32_bf16 v[116:119], v[168:171], v[184:187], v[116:119]
	v_mfma_f32_16x16x32_bf16 v[104:107], v[176:179], v[184:187], v[104:107]
	v_mfma_f32_16x16x32_bf16 v[100:103], v[168:171], v[192:195], v[100:103]
	v_mfma_f32_16x16x32_bf16 v[88:91], v[176:179], v[192:195], v[88:91]
	v_mfma_f32_16x16x32_bf16 v[84:87], v[168:171], v[200:203], v[84:87]
	v_mfma_f32_16x16x32_bf16 v[72:75], v[176:179], v[200:203], v[72:75]
	v_mfma_f32_16x16x32_bf16 v[68:71], v[168:171], v[208:211], v[68:71]
	v_mfma_f32_16x16x32_bf16 v[64:67], v[176:179], v[208:211], v[64:67]
	s_setprio 0
	s_barrier
	s_add_i32 s40, s64, s70
	s_mov_b32 m0, s40
	ds_read_b128 v[180:183], v163 offset:49152
	ds_read_b128 v[184:187], v163 offset:50176
	ds_read_b128 v[188:191], v163 offset:51200
	ds_read_b128 v[192:195], v163 offset:52224
	ds_read_b128 v[196:199], v163 offset:53248
	ds_read_b128 v[200:203], v163 offset:54272
	ds_read_b128 v[204:207], v163 offset:55296
	ds_read_b128 v[208:211], v163 offset:56320
	global_load_lds_dwordx4 v144, s[98:99]
	s_add_i32 m0, s40, 0x2000
	s_add_u32 s38, s38, 0x40080
	s_addc_u32 s39, s39, 0
	s_add_i32 s40, s65, s70
	global_load_lds_dwordx4 v146, s[98:99]
	s_mov_b32 m0, s40
	s_nop 0
	global_load_lds_dwordx4 v144, s[38:39]
	s_add_i32 m0, s40, 0x2000
	s_nop 0
	global_load_lds_dwordx4 v146, s[38:39]
	s_mov_b32 m0, s52
	s_nop 0
	global_load_lds_dwordx4 v144, s[100:101]
	s_mov_b32 m0, s53
	s_nop 0
	global_load_lds_dwordx4 v146, s[100:101]
	s_waitcnt vmcnt(8)
	s_waitcnt lgkmcnt(0)
	s_barrier
	s_setprio 1
	s_waitcnt lgkmcnt(0)
	v_mfma_f32_16x16x32_bf16 v[60:63], v[128:131], v[180:183], v[60:63]
	v_mfma_f32_16x16x32_bf16 v[56:59], v[136:139], v[180:183], v[56:59]
	v_mfma_f32_16x16x32_bf16 v[48:51], v[128:131], v[188:191], v[48:51]
	v_mfma_f32_16x16x32_bf16 v[44:47], v[136:139], v[188:191], v[44:47]
	v_mfma_f32_16x16x32_bf16 v[32:35], v[128:131], v[196:199], v[32:35]
	v_mfma_f32_16x16x32_bf16 v[28:31], v[136:139], v[196:199], v[28:31]
	v_mfma_f32_16x16x32_bf16 v[16:19], v[128:131], v[204:207], v[16:19]
	v_mfma_f32_16x16x32_bf16 v[12:15], v[136:139], v[204:207], v[12:15]
	v_mfma_f32_16x16x32_bf16 v[60:63], v[132:135], v[184:187], v[60:63]
	v_mfma_f32_16x16x32_bf16 v[56:59], v[140:143], v[184:187], v[56:59]
	v_mfma_f32_16x16x32_bf16 v[48:51], v[132:135], v[192:195], v[48:51]
	v_mfma_f32_16x16x32_bf16 v[44:47], v[140:143], v[192:195], v[44:47]
	v_mfma_f32_16x16x32_bf16 v[32:35], v[132:135], v[200:203], v[32:35]
	v_mfma_f32_16x16x32_bf16 v[28:31], v[140:143], v[200:203], v[28:31]
	v_mfma_f32_16x16x32_bf16 v[16:19], v[132:135], v[208:211], v[16:19]
	v_mfma_f32_16x16x32_bf16 v[12:15], v[140:143], v[208:211], v[12:15]
	s_setprio 0
	s_setprio 1
	v_mfma_f32_16x16x32_bf16 v[52:55], v[164:167], v[180:183], v[52:55]
	v_mfma_f32_16x16x32_bf16 v[40:43], v[172:175], v[180:183], v[40:43]
	v_mfma_f32_16x16x32_bf16 v[36:39], v[164:167], v[188:191], v[36:39]
	v_mfma_f32_16x16x32_bf16 v[24:27], v[172:175], v[188:191], v[24:27]
	v_mfma_f32_16x16x32_bf16 v[20:23], v[164:167], v[196:199], v[20:23]
	v_mfma_f32_16x16x32_bf16 v[8:11], v[172:175], v[196:199], v[8:11]
	v_mfma_f32_16x16x32_bf16 v[4:7], v[164:167], v[204:207], v[4:7]
	v_mfma_f32_16x16x32_bf16 v[0:3], v[172:175], v[204:207], v[0:3]
	v_mfma_f32_16x16x32_bf16 v[52:55], v[168:171], v[184:187], v[52:55]
	v_mfma_f32_16x16x32_bf16 v[40:43], v[176:179], v[184:187], v[40:43]
	v_mfma_f32_16x16x32_bf16 v[36:39], v[168:171], v[192:195], v[36:39]
	v_mfma_f32_16x16x32_bf16 v[24:27], v[176:179], v[192:195], v[24:27]
	v_mfma_f32_16x16x32_bf16 v[20:23], v[168:171], v[200:203], v[20:23]
	v_mfma_f32_16x16x32_bf16 v[8:11], v[176:179], v[200:203], v[8:11]
	v_mfma_f32_16x16x32_bf16 v[4:7], v[168:171], v[208:211], v[4:7]
	v_mfma_f32_16x16x32_bf16 v[0:3], v[176:179], v[208:211], v[0:3]
	s_setprio 0
	s_barrier
	s_add_i32 s63, s63, 2
	s_add_u32 s61, s61, 0x100
	s_addc_u32 s62, s62, 0
	s_add_u32 s36, s36, 0x100
	s_addc_u32 s37, s37, 0
	s_cmp_gt_u32 s63, 13
	s_cbranch_scc0 .LBB0_574
	s_and_b64 vcc, exec, s[8:9]
	s_cbranch_vccz .LBB0_577
	s_barrier

.LBB0_705:
	ds_read_b128 v[48:51], v238
	ds_read_b128 v[52:55], v238 offset:1024
	ds_read_b128 v[56:59], v238 offset:2048
	ds_read_b128 v[60:63], v238 offset:3072
	ds_read_b128 v[64:67], v239
	ds_read_b128 v[68:71], v239 offset:1024
	ds_read_b128 v[72:75], v239 offset:2048
	ds_read_b128 v[76:79], v239 offset:3072
	s_add_u32 s56, s10, 0xfffc0080
	s_addc_u32 s57, s11, -1
	s_cmp_eq_u32 s82, 12
	s_cselect_b32 s59, s43, s57
	s_cselect_b32 s58, s45, s56
	s_cselect_b32 s57, s55, s81
	s_cselect_b32 s56, s79, s80
	s_add_i32 m0, s63, 0xc000
	ds_read_b128 v[144:147], v240
	ds_read_b128 v[148:151], v240 offset:1024
	ds_read_b128 v[152:155], v240 offset:2048
	ds_read_b128 v[156:159], v240 offset:3072
	ds_read_b128 v[160:163], v240 offset:4096
	ds_read_b128 v[164:167], v240 offset:5120
	ds_read_b128 v[168:171], v240 offset:6144
	ds_read_b128 v[172:175], v240 offset:7168
	global_load_lds_dwordx4 v220, s[10:11]
	s_add_i32 m0, s63, 0xe000
	s_nop 0
	global_load_lds_dwordx4 v218, s[10:11]
	s_waitcnt vmcnt(8)
	s_waitcnt lgkmcnt(0)
	s_barrier
	s_setprio 1
	s_waitcnt lgkmcnt(0)
	v_mfma_f32_16x16x32_bf16 v[188:191], v[48:51], v[144:147], v[188:191]
	v_mfma_f32_16x16x32_bf16 v[92:95], v[56:59], v[144:147], v[92:95]
	v_mfma_f32_16x16x32_bf16 v[180:183], v[48:51], v[152:155], v[180:183]
	v_mfma_f32_16x16x32_bf16 v[84:87], v[56:59], v[152:155], v[84:87]
	v_mfma_f32_16x16x32_bf16 v[140:143], v[48:51], v[160:163], v[140:143]
	v_mfma_f32_16x16x32_bf16 v[44:47], v[56:59], v[160:163], v[44:47]
	v_mfma_f32_16x16x32_bf16 v[136:139], v[48:51], v[168:171], v[136:139]
	v_mfma_f32_16x16x32_bf16 v[40:43], v[56:59], v[168:171], v[40:43]
	v_mfma_f32_16x16x32_bf16 v[188:191], v[52:55], v[148:151], v[188:191]
	v_mfma_f32_16x16x32_bf16 v[92:95], v[60:63], v[148:151], v[92:95]
	v_mfma_f32_16x16x32_bf16 v[180:183], v[52:55], v[156:159], v[180:183]
	v_mfma_f32_16x16x32_bf16 v[84:87], v[60:63], v[156:159], v[84:87]
	v_mfma_f32_16x16x32_bf16 v[140:143], v[52:55], v[164:167], v[140:143]
	v_mfma_f32_16x16x32_bf16 v[44:47], v[60:63], v[164:167], v[44:47]
	v_mfma_f32_16x16x32_bf16 v[136:139], v[52:55], v[172:175], v[136:139]
	v_mfma_f32_16x16x32_bf16 v[40:43], v[60:63], v[172:175], v[40:43]
	s_setprio 0
	s_setprio 1
	v_mfma_f32_16x16x32_bf16 v[184:187], v[64:67], v[144:147], v[184:187]
	v_mfma_f32_16x16x32_bf16 v[88:91], v[72:75], v[144:147], v[88:91]
	v_mfma_f32_16x16x32_bf16 v[80:83], v[72:75], v[152:155], v[80:83]
	v_mfma_f32_16x16x32_bf16 v[132:135], v[64:67], v[160:163], v[132:135]
	v_mfma_f32_16x16x32_bf16 v[36:39], v[72:75], v[160:163], v[36:39]
	v_mfma_f32_16x16x32_bf16 v[128:131], v[64:67], v[168:171], v[128:131]
	v_mfma_f32_16x16x32_bf16 v[32:35], v[72:75], v[168:171], v[32:35]
	v_mfma_f32_16x16x32_bf16 v[184:187], v[68:71], v[148:151], v[184:187]
	v_mfma_f32_16x16x32_bf16 v[88:91], v[76:79], v[148:151], v[88:91]
	v_mfma_f32_16x16x32_bf16 v[144:147], v[64:67], v[152:155], v[176:179]
	v_mfma_f32_16x16x32_bf16 v[80:83], v[76:79], v[156:159], v[80:83]
	v_mfma_f32_16x16x32_bf16 v[132:135], v[68:71], v[164:167], v[132:135]
	v_mfma_f32_16x16x32_bf16 v[36:39], v[76:79], v[164:167], v[36:39]
	v_mfma_f32_16x16x32_bf16 v[128:131], v[68:71], v[172:175], v[128:131]
	v_mfma_f32_16x16x32_bf16 v[32:35], v[76:79], v[172:175], v[32:35]
	v_mfma_f32_16x16x32_bf16 v[144:147], v[68:71], v[156:159], v[144:147]
	s_setprio 0
	s_barrier
	s_add_i32 s83, s73, s86
	s_add_u32 s98, s56, s18
	s_addc_u32 s99, s57, s19
	s_add_u32 s100, s58, s18
	s_addc_u32 s101, s59, s19
	s_mov_b32 m0, s83
	ds_read_b128 v[148:151], v240 offset:16384
	ds_read_b128 v[152:155], v240 offset:17408
	ds_read_b128 v[156:159], v240 offset:18432
	ds_read_b128 v[160:163], v240 offset:19456
	ds_read_b128 v[164:167], v240 offset:20480
	ds_read_b128 v[168:171], v240 offset:21504
	ds_read_b128 v[172:175], v240 offset:22528
	ds_read_b128 v[176:179], v240 offset:23552
	global_load_lds_dwordx4 v204, s[56:57]
	s_add_i32 m0, s83, 0x2000
	s_add_u32 s84, s56, 0x40000
	s_addc_u32 s85, s57, 0
	s_add_i32 s83, s74, s86
	global_load_lds_dwordx4 v208, s[56:57]
	s_mov_b32 m0, s83
	s_nop 0
	global_load_lds_dwordx4 v204, s[84:85]
	s_add_i32 m0, s83, 0x2000
	s_nop 0
	global_load_lds_dwordx4 v208, s[84:85]
	s_mov_b32 m0, s63
	s_nop 0
	global_load_lds_dwordx4 v202, s[58:59]
	s_mov_b32 m0, s64
	s_nop 0
	global_load_lds_dwordx4 v206, s[58:59]
	s_waitcnt vmcnt(8)
	s_waitcnt lgkmcnt(0)
	s_barrier
	s_setprio 1
	s_waitcnt lgkmcnt(0)
	v_mfma_f32_16x16x32_bf16 v[124:127], v[48:51], v[148:151], v[124:127]
	v_mfma_f32_16x16x32_bf16 v[28:31], v[56:59], v[148:151], v[28:31]
	v_mfma_f32_16x16x32_bf16 v[116:119], v[48:51], v[156:159], v[116:119]
	v_mfma_f32_16x16x32_bf16 v[20:23], v[56:59], v[156:159], v[20:23]
	v_mfma_f32_16x16x32_bf16 v[108:111], v[48:51], v[164:167], v[108:111]
	v_mfma_f32_16x16x32_bf16 v[12:15], v[56:59], v[164:167], v[12:15]
	v_mfma_f32_16x16x32_bf16 v[8:11], v[56:59], v[172:175], v[8:11]
	v_mfma_f32_16x16x32_bf16 v[124:127], v[52:55], v[152:155], v[124:127]
	v_mfma_f32_16x16x32_bf16 v[28:31], v[60:63], v[152:155], v[28:31]
	v_mfma_f32_16x16x32_bf16 v[116:119], v[52:55], v[160:163], v[116:119]
	v_mfma_f32_16x16x32_bf16 v[20:23], v[60:63], v[160:163], v[20:23]
	v_mfma_f32_16x16x32_bf16 v[108:111], v[52:55], v[168:171], v[108:111]
	v_mfma_f32_16x16x32_bf16 v[12:15], v[60:63], v[168:171], v[12:15]
	v_mfma_f32_16x16x32_bf16 v[48:51], v[48:51], v[172:175], v[104:107]
	v_mfma_f32_16x16x32_bf16 v[8:11], v[60:63], v[176:179], v[8:11]
	v_mfma_f32_16x16x32_bf16 v[48:51], v[52:55], v[176:179], v[48:51]
	s_setprio 0
	s_setprio 1
	v_mfma_f32_16x16x32_bf16 v[24:27], v[72:75], v[148:151], v[24:27]
	v_mfma_f32_16x16x32_bf16 v[16:19], v[72:75], v[156:159], v[16:19]
	v_mfma_f32_16x16x32_bf16 v[4:7], v[72:75], v[164:167], v[4:7]
	v_mfma_f32_16x16x32_bf16 v[0:3], v[72:75], v[172:175], v[0:3]
	v_mfma_f32_16x16x32_bf16 v[52:55], v[64:67], v[148:151], v[120:123]
	v_mfma_f32_16x16x32_bf16 v[24:27], v[76:79], v[152:155], v[24:27]
	v_mfma_f32_16x16x32_bf16 v[56:59], v[64:67], v[156:159], v[112:115]
	v_mfma_f32_16x16x32_bf16 v[16:19], v[76:79], v[160:163], v[16:19]
	v_mfma_f32_16x16x32_bf16 v[60:63], v[64:67], v[164:167], v[100:103]
	v_mfma_f32_16x16x32_bf16 v[4:7], v[76:79], v[168:171], v[4:7]
	v_mfma_f32_16x16x32_bf16 v[64:67], v[64:67], v[172:175], v[96:99]
	v_mfma_f32_16x16x32_bf16 v[0:3], v[76:79], v[176:179], v[0:3]
	v_mfma_f32_16x16x32_bf16 v[52:55], v[68:71], v[152:155], v[52:55]
	v_mfma_f32_16x16x32_bf16 v[56:59], v[68:71], v[160:163], v[56:59]
	v_mfma_f32_16x16x32_bf16 v[60:63], v[68:71], v[168:171], v[60:63]
	v_mfma_f32_16x16x32_bf16 v[64:67], v[68:71], v[176:179], v[64:67]
	s_setprio 0
	s_barrier
	s_add_i32 s83, 0, 0x18000
	s_add_i32 s84, 0, 0x1c000
	v_add_u32_e32 v96, s83, v215
	v_add_u32_e32 v100, s84, v215
	ds_read_b128 v[68:71], v96
	ds_read_b128 v[72:75], v96 offset:1024
	ds_read_b128 v[76:79], v96 offset:2048
	ds_read_b128 v[96:99], v96 offset:3072
	ds_read_b128 v[148:151], v100
	ds_read_b128 v[152:155], v100 offset:1024
	ds_read_b128 v[156:159], v100 offset:2048
	ds_read_b128 v[160:163], v100 offset:3072
	s_add_u32 s58, s58, 0x40000
	s_addc_u32 s59, s59, 0
	s_mov_b32 m0, s65
	ds_read_b128 v[100:103], v240 offset:32768
	ds_read_b128 v[104:107], v240 offset:33792
	ds_read_b128 v[112:115], v240 offset:34816
	ds_read_b128 v[120:123], v240 offset:35840
	ds_read_b128 v[164:167], v240 offset:36864
	ds_read_b128 v[168:171], v240 offset:37888
	ds_read_b128 v[172:175], v240 offset:38912
	ds_read_b128 v[192:195], v240 offset:39936
	global_load_lds_dwordx4 v202, s[58:59]
	s_mov_b32 m0, s66
	s_nop 0
	global_load_lds_dwordx4 v206, s[58:59]
	s_waitcnt vmcnt(8)
	s_waitcnt lgkmcnt(0)
	s_barrier
	s_setprio 1
	s_waitcnt lgkmcnt(0)
	v_mfma_f32_16x16x32_bf16 v[176:179], v[68:71], v[100:103], v[188:191]
	v_mfma_f32_16x16x32_bf16 v[188:191], v[72:75], v[104:107], v[176:179]
	v_mfma_f32_16x16x32_bf16 v[92:95], v[76:79], v[100:103], v[92:95]
	v_mfma_f32_16x16x32_bf16 v[176:179], v[68:71], v[112:115], v[180:183]
	v_mfma_f32_16x16x32_bf16 v[84:87], v[76:79], v[112:115], v[84:87]
	v_mfma_f32_16x16x32_bf16 v[140:143], v[68:71], v[164:167], v[140:143]
	v_mfma_f32_16x16x32_bf16 v[44:47], v[76:79], v[164:167], v[44:47]
	v_mfma_f32_16x16x32_bf16 v[136:139], v[68:71], v[172:175], v[136:139]
	v_mfma_f32_16x16x32_bf16 v[40:43], v[76:79], v[172:175], v[40:43]
	v_mfma_f32_16x16x32_bf16 v[92:95], v[96:99], v[104:107], v[92:95]
	v_mfma_f32_16x16x32_bf16 v[180:183], v[72:75], v[120:123], v[176:179]
	v_mfma_f32_16x16x32_bf16 v[84:87], v[96:99], v[120:123], v[84:87]
	v_mfma_f32_16x16x32_bf16 v[140:143], v[72:75], v[168:171], v[140:143]
	v_mfma_f32_16x16x32_bf16 v[44:47], v[96:99], v[168:171], v[44:47]
	v_mfma_f32_16x16x32_bf16 v[136:139], v[72:75], v[192:195], v[136:139]
	v_mfma_f32_16x16x32_bf16 v[40:43], v[96:99], v[192:195], v[40:43]
	s_setprio 0
	s_setprio 1
	v_mfma_f32_16x16x32_bf16 v[176:179], v[148:151], v[100:103], v[184:187]
	v_mfma_f32_16x16x32_bf16 v[88:91], v[156:159], v[100:103], v[88:91]
	v_mfma_f32_16x16x32_bf16 v[100:103], v[148:151], v[112:115], v[144:147]
	v_mfma_f32_16x16x32_bf16 v[184:187], v[152:155], v[104:107], v[176:179]
	v_mfma_f32_16x16x32_bf16 v[176:179], v[152:155], v[120:123], v[100:103]
	v_mfma_f32_16x16x32_bf16 v[100:103], v[148:151], v[164:167], v[132:135]
	v_mfma_f32_16x16x32_bf16 v[80:83], v[156:159], v[112:115], v[80:83]
	v_mfma_f32_16x16x32_bf16 v[132:135], v[152:155], v[168:171], v[100:103]
	v_mfma_f32_16x16x32_bf16 v[36:39], v[156:159], v[164:167], v[36:39]
	v_mfma_f32_16x16x32_bf16 v[100:103], v[148:151], v[172:175], v[128:131]
	v_mfma_f32_16x16x32_bf16 v[32:35], v[156:159], v[172:175], v[32:35]
	v_mfma_f32_16x16x32_bf16 v[88:91], v[160:163], v[104:107], v[88:91]
	v_mfma_f32_16x16x32_bf16 v[80:83], v[160:163], v[120:123], v[80:83]
	v_mfma_f32_16x16x32_bf16 v[36:39], v[160:163], v[168:171], v[36:39]
	v_mfma_f32_16x16x32_bf16 v[128:131], v[152:155], v[192:195], v[100:103]
	v_mfma_f32_16x16x32_bf16 v[32:35], v[160:163], v[192:195], v[32:35]
	s_setprio 0
	s_barrier
	s_add_i32 s58, s83, s86
	s_mov_b32 m0, s58
	ds_read_b128 v[100:103], v240 offset:49152
	ds_read_b128 v[112:115], v240 offset:50176
	ds_read_b128 v[144:147], v240 offset:51200
	ds_read_b128 v[164:167], v240 offset:52224
	ds_read_b128 v[168:171], v240 offset:53248
	ds_read_b128 v[172:175], v240 offset:54272
	ds_read_b128 v[192:195], v240 offset:55296
	ds_read_b128 v[196:199], v240 offset:56320
	global_load_lds_dwordx4 v204, s[98:99]
	s_add_i32 m0, s58, 0x2000
	s_add_u32 s56, s56, 0x40080
	s_addc_u32 s57, s57, 0
	s_add_i32 s58, s84, s86
	global_load_lds_dwordx4 v208, s[98:99]
	s_mov_b32 m0, s58
	s_nop 0
	global_load_lds_dwordx4 v204, s[56:57]
	s_add_i32 m0, s58, 0x2000
	s_nop 0
	global_load_lds_dwordx4 v208, s[56:57]
	s_mov_b32 m0, s68
	s_nop 0
	global_load_lds_dwordx4 v202, s[100:101]
	s_mov_b32 m0, s69
	s_nop 0
	global_load_lds_dwordx4 v206, s[100:101]
	s_waitcnt vmcnt(8)
	s_waitcnt lgkmcnt(0)
	s_barrier
	s_setprio 1
	s_waitcnt lgkmcnt(0)
	v_mfma_f32_16x16x32_bf16 v[104:107], v[68:71], v[100:103], v[124:127]
	v_mfma_f32_16x16x32_bf16 v[124:127], v[72:75], v[112:115], v[104:107]
	v_mfma_f32_16x16x32_bf16 v[104:107], v[68:71], v[144:147], v[116:119]
	v_mfma_f32_16x16x32_bf16 v[28:31], v[76:79], v[100:103], v[28:31]
	v_mfma_f32_16x16x32_bf16 v[116:119], v[72:75], v[164:167], v[104:107]
	v_mfma_f32_16x16x32_bf16 v[20:23], v[76:79], v[144:147], v[20:23]
	v_mfma_f32_16x16x32_bf16 v[104:107], v[68:71], v[168:171], v[108:111]
	v_mfma_f32_16x16x32_bf16 v[12:15], v[76:79], v[168:171], v[12:15]
	v_mfma_f32_16x16x32_bf16 v[48:51], v[68:71], v[192:195], v[48:51]
	v_mfma_f32_16x16x32_bf16 v[8:11], v[76:79], v[192:195], v[8:11]
	v_mfma_f32_16x16x32_bf16 v[28:31], v[96:99], v[112:115], v[28:31]
	v_mfma_f32_16x16x32_bf16 v[20:23], v[96:99], v[164:167], v[20:23]
	v_mfma_f32_16x16x32_bf16 v[108:111], v[72:75], v[172:175], v[104:107]
	v_mfma_f32_16x16x32_bf16 v[12:15], v[96:99], v[172:175], v[12:15]
	v_mfma_f32_16x16x32_bf16 v[104:107], v[72:75], v[196:199], v[48:51]
	v_mfma_f32_16x16x32_bf16 v[8:11], v[96:99], v[196:199], v[8:11]
	s_setprio 0
	s_setprio 1
	v_mfma_f32_16x16x32_bf16 v[48:51], v[148:151], v[100:103], v[52:55]
	v_mfma_f32_16x16x32_bf16 v[120:123], v[152:155], v[112:115], v[48:51]
	v_mfma_f32_16x16x32_bf16 v[24:27], v[156:159], v[100:103], v[24:27]
	v_mfma_f32_16x16x32_bf16 v[48:51], v[148:151], v[144:147], v[56:59]
	v_mfma_f32_16x16x32_bf16 v[24:27], v[160:163], v[112:115], v[24:27]
	v_mfma_f32_16x16x32_bf16 v[112:115], v[152:155], v[164:167], v[48:51]
	v_mfma_f32_16x16x32_bf16 v[48:51], v[148:151], v[168:171], v[60:63]
	v_mfma_f32_16x16x32_bf16 v[16:19], v[156:159], v[144:147], v[16:19]
	v_mfma_f32_16x16x32_bf16 v[100:103], v[152:155], v[172:175], v[48:51]
	v_mfma_f32_16x16x32_bf16 v[4:7], v[156:159], v[168:171], v[4:7]
	v_mfma_f32_16x16x32_bf16 v[48:51], v[148:151], v[192:195], v[64:67]
	v_mfma_f32_16x16x32_bf16 v[0:3], v[156:159], v[192:195], v[0:3]
	v_mfma_f32_16x16x32_bf16 v[16:19], v[160:163], v[164:167], v[16:19]
	v_mfma_f32_16x16x32_bf16 v[4:7], v[160:163], v[172:175], v[4:7]
	v_mfma_f32_16x16x32_bf16 v[96:99], v[152:155], v[196:199], v[48:51]
	v_mfma_f32_16x16x32_bf16 v[0:3], v[160:163], v[196:199], v[0:3]
	s_setprio 0
	s_barrier
	s_add_i32 s82, s82, 2
	s_add_u32 s80, s80, 0x100
	s_addc_u32 s81, s81, 0
	s_add_u32 s10, s10, 0x100
	s_addc_u32 s11, s11, 0
	s_cmp_gt_u32 s82, 13
	s_cbranch_scc0 .LBB0_705
	s_and_b64 vcc, exec, s[20:21]
	s_cbranch_vccz .LBB0_708
	s_barrier

.LBB0_815:
	ds_read_b128 v[64:67], v165
	ds_read_b128 v[108:111], v165 offset:1024
	ds_read_b128 v[116:119], v165 offset:2048
	ds_read_b128 v[128:131], v165 offset:3072
	ds_read_b128 v[156:159], v166
	ds_read_b128 v[168:171], v166 offset:1024
	ds_read_b128 v[172:175], v166 offset:2048
	ds_read_b128 v[176:179], v166 offset:3072
	s_add_u32 s28, s26, 0x100
	s_addc_u32 s29, s27, 0
	s_cmp_eq_u32 s65, 40
	s_cselect_b32 s35, s59, s29
	s_cselect_b32 s34, s60, s28
	s_cselect_b32 s31, s61, s64
	s_cselect_b32 s30, s62, s63
	v_lshl_add_u64 v[160:161], s[26:27], 0, v[150:151]
	s_add_i32 m0, s40, 0xc000
	ds_read_b128 v[180:183], v167
	ds_read_b128 v[184:187], v167 offset:1024
	ds_read_b128 v[188:191], v167 offset:2048
	ds_read_b128 v[192:195], v167 offset:3072
	ds_read_b128 v[196:199], v167 offset:4096
	ds_read_b128 v[200:203], v167 offset:5120
	ds_read_b128 v[204:207], v167 offset:6144
	ds_read_b128 v[208:211], v167 offset:7168
	global_load_lds_dwordx4 v[160:161], off
	v_lshl_add_u64 v[160:161], s[26:27], 0, v[148:149]
	s_add_i32 m0, s40, 0xe000
	s_nop 0
	global_load_lds_dwordx4 v[160:161], off
	s_waitcnt vmcnt(8)
	s_waitcnt lgkmcnt(0)
	s_barrier
	s_setprio 1
	s_waitcnt lgkmcnt(0)
	v_mfma_f32_16x16x32_bf16 v[140:143], v[64:67], v[180:183], v[140:143]
	v_mfma_f32_16x16x32_bf16 v[136:139], v[116:119], v[180:183], v[136:139]
	v_mfma_f32_16x16x32_bf16 v[120:123], v[64:67], v[188:191], v[120:123]
	v_mfma_f32_16x16x32_bf16 v[112:115], v[116:119], v[188:191], v[112:115]
	v_mfma_f32_16x16x32_bf16 v[96:99], v[64:67], v[196:199], v[96:99]
	v_mfma_f32_16x16x32_bf16 v[92:95], v[116:119], v[196:199], v[92:95]
	v_mfma_f32_16x16x32_bf16 v[80:83], v[64:67], v[204:207], v[80:83]
	v_mfma_f32_16x16x32_bf16 v[76:79], v[116:119], v[204:207], v[76:79]
	v_mfma_f32_16x16x32_bf16 v[140:143], v[108:111], v[184:187], v[140:143]
	v_mfma_f32_16x16x32_bf16 v[136:139], v[128:131], v[184:187], v[136:139]
	v_mfma_f32_16x16x32_bf16 v[120:123], v[108:111], v[192:195], v[120:123]
	v_mfma_f32_16x16x32_bf16 v[112:115], v[128:131], v[192:195], v[112:115]
	v_mfma_f32_16x16x32_bf16 v[96:99], v[108:111], v[200:203], v[96:99]
	v_mfma_f32_16x16x32_bf16 v[92:95], v[128:131], v[200:203], v[92:95]
	v_mfma_f32_16x16x32_bf16 v[80:83], v[108:111], v[208:211], v[80:83]
	v_mfma_f32_16x16x32_bf16 v[76:79], v[128:131], v[208:211], v[76:79]
	s_setprio 0
	s_setprio 1
	v_mfma_f32_16x16x32_bf16 v[132:135], v[156:159], v[180:183], v[132:135]
	v_mfma_f32_16x16x32_bf16 v[124:127], v[172:175], v[180:183], v[124:127]
	v_mfma_f32_16x16x32_bf16 v[104:107], v[156:159], v[188:191], v[104:107]
	v_mfma_f32_16x16x32_bf16 v[100:103], v[172:175], v[188:191], v[100:103]
	v_mfma_f32_16x16x32_bf16 v[88:91], v[156:159], v[196:199], v[88:91]
	v_mfma_f32_16x16x32_bf16 v[84:87], v[172:175], v[196:199], v[84:87]
	v_mfma_f32_16x16x32_bf16 v[72:75], v[156:159], v[204:207], v[72:75]
	v_mfma_f32_16x16x32_bf16 v[68:71], v[172:175], v[204:207], v[68:71]
	v_mfma_f32_16x16x32_bf16 v[132:135], v[168:171], v[184:187], v[132:135]
	v_mfma_f32_16x16x32_bf16 v[124:127], v[176:179], v[184:187], v[124:127]
	v_mfma_f32_16x16x32_bf16 v[104:107], v[168:171], v[192:195], v[104:107]
	v_mfma_f32_16x16x32_bf16 v[100:103], v[176:179], v[192:195], v[100:103]
	v_mfma_f32_16x16x32_bf16 v[88:91], v[168:171], v[200:203], v[88:91]
	v_mfma_f32_16x16x32_bf16 v[84:87], v[176:179], v[200:203], v[84:87]
	v_mfma_f32_16x16x32_bf16 v[72:75], v[168:171], v[208:211], v[72:75]
	v_mfma_f32_16x16x32_bf16 v[68:71], v[176:179], v[208:211], v[68:71]
	s_setprio 0
	s_barrier
	s_add_i32 s26, s49, s68
	s_add_u32 s98, s30, s8
	s_addc_u32 s99, s31, s9
	s_add_u32 s100, s34, s8
	s_addc_u32 s101, s35, s9
	s_mov_b32 m0, s26
	ds_read_b128 v[180:183], v167 offset:16384
	ds_read_b128 v[184:187], v167 offset:17408
	ds_read_b128 v[188:191], v167 offset:18432
	ds_read_b128 v[192:195], v167 offset:19456
	ds_read_b128 v[196:199], v167 offset:20480
	ds_read_b128 v[200:203], v167 offset:21504
	ds_read_b128 v[204:207], v167 offset:22528
	ds_read_b128 v[208:211], v167 offset:23552
	global_load_lds_dwordx4 v144, s[30:31]
	s_add_i32 m0, s26, 0x2000
	s_add_u32 s26, s30, 0xb0000
	s_addc_u32 s27, s31, 0
	s_add_i32 s66, s50, s68
	global_load_lds_dwordx4 v146, s[30:31]
	s_mov_b32 m0, s66
	s_nop 0
	global_load_lds_dwordx4 v144, s[26:27]
	s_add_i32 m0, s66, 0x2000
	s_nop 0
	global_load_lds_dwordx4 v146, s[26:27]
	s_mov_b32 m0, s40
	s_nop 0
	global_load_lds_dwordx4 v144, s[34:35]
	s_mov_b32 m0, s41
	s_nop 0
	global_load_lds_dwordx4 v146, s[34:35]
	s_waitcnt vmcnt(8)
	s_waitcnt lgkmcnt(0)
	s_barrier
	s_setprio 1
	s_waitcnt lgkmcnt(0)
	v_mfma_f32_16x16x32_bf16 v[60:63], v[64:67], v[180:183], v[60:63]
	v_mfma_f32_16x16x32_bf16 v[56:59], v[116:119], v[180:183], v[56:59]
	v_mfma_f32_16x16x32_bf16 v[44:47], v[64:67], v[188:191], v[44:47]
	v_mfma_f32_16x16x32_bf16 v[40:43], v[116:119], v[188:191], v[40:43]
	v_mfma_f32_16x16x32_bf16 v[28:31], v[64:67], v[196:199], v[28:31]
	v_mfma_f32_16x16x32_bf16 v[24:27], v[116:119], v[196:199], v[24:27]
	v_mfma_f32_16x16x32_bf16 v[12:15], v[64:67], v[204:207], v[12:15]
	v_mfma_f32_16x16x32_bf16 v[8:11], v[116:119], v[204:207], v[8:11]
	v_mfma_f32_16x16x32_bf16 v[60:63], v[108:111], v[184:187], v[60:63]
	v_mfma_f32_16x16x32_bf16 v[56:59], v[128:131], v[184:187], v[56:59]
	v_mfma_f32_16x16x32_bf16 v[44:47], v[108:111], v[192:195], v[44:47]
	v_mfma_f32_16x16x32_bf16 v[40:43], v[128:131], v[192:195], v[40:43]
	v_mfma_f32_16x16x32_bf16 v[28:31], v[108:111], v[200:203], v[28:31]
	v_mfma_f32_16x16x32_bf16 v[24:27], v[128:131], v[200:203], v[24:27]
	v_mfma_f32_16x16x32_bf16 v[12:15], v[108:111], v[208:211], v[12:15]
	v_mfma_f32_16x16x32_bf16 v[8:11], v[128:131], v[208:211], v[8:11]
	s_setprio 0
	s_setprio 1
	v_mfma_f32_16x16x32_bf16 v[52:55], v[156:159], v[180:183], v[52:55]
	v_mfma_f32_16x16x32_bf16 v[48:51], v[172:175], v[180:183], v[48:51]
	v_mfma_f32_16x16x32_bf16 v[36:39], v[156:159], v[188:191], v[36:39]
	v_mfma_f32_16x16x32_bf16 v[32:35], v[172:175], v[188:191], v[32:35]
	v_mfma_f32_16x16x32_bf16 v[20:23], v[156:159], v[196:199], v[20:23]
	v_mfma_f32_16x16x32_bf16 v[16:19], v[172:175], v[196:199], v[16:19]
	v_mfma_f32_16x16x32_bf16 v[4:7], v[156:159], v[204:207], v[4:7]
	v_mfma_f32_16x16x32_bf16 v[0:3], v[172:175], v[204:207], v[0:3]
	v_mfma_f32_16x16x32_bf16 v[52:55], v[168:171], v[184:187], v[52:55]
	v_mfma_f32_16x16x32_bf16 v[48:51], v[176:179], v[184:187], v[48:51]
	v_mfma_f32_16x16x32_bf16 v[36:39], v[168:171], v[192:195], v[36:39]
	v_mfma_f32_16x16x32_bf16 v[32:35], v[176:179], v[192:195], v[32:35]
	v_mfma_f32_16x16x32_bf16 v[20:23], v[168:171], v[200:203], v[20:23]
	v_mfma_f32_16x16x32_bf16 v[16:19], v[176:179], v[200:203], v[16:19]
	v_mfma_f32_16x16x32_bf16 v[4:7], v[168:171], v[208:211], v[4:7]
	v_mfma_f32_16x16x32_bf16 v[0:3], v[176:179], v[208:211], v[0:3]
	s_setprio 0
	s_barrier
	s_add_i32 s66, 0, 0x18000
	s_add_i32 s67, 0, 0x1c000
	v_add_u32_e32 v128, s66, v163
	v_add_u32_e32 v176, s67, v163
	ds_read_b128 v[64:67], v128
	ds_read_b128 v[108:111], v128 offset:1024
	ds_read_b128 v[116:119], v128 offset:2048
	ds_read_b128 v[128:131], v128 offset:3072
	ds_read_b128 v[156:159], v176
	ds_read_b128 v[168:171], v176 offset:1024
	ds_read_b128 v[172:175], v176 offset:2048
	ds_read_b128 v[176:179], v176 offset:3072
	s_add_u32 s26, s34, 0xb0000
	s_addc_u32 s27, s35, 0
	s_mov_b32 m0, s42
	ds_read_b128 v[180:183], v167 offset:32768
	ds_read_b128 v[184:187], v167 offset:33792
	ds_read_b128 v[188:191], v167 offset:34816
	ds_read_b128 v[192:195], v167 offset:35840
	ds_read_b128 v[196:199], v167 offset:36864
	ds_read_b128 v[200:203], v167 offset:37888
	ds_read_b128 v[204:207], v167 offset:38912
	ds_read_b128 v[208:211], v167 offset:39936
	global_load_lds_dwordx4 v144, s[26:27]
	s_mov_b32 m0, s43
	s_nop 0
	global_load_lds_dwordx4 v146, s[26:27]
	s_waitcnt vmcnt(8)
	s_waitcnt lgkmcnt(0)
	s_barrier
	s_setprio 1
	s_waitcnt lgkmcnt(0)
	v_mfma_f32_16x16x32_bf16 v[140:143], v[64:67], v[180:183], v[140:143]
	v_mfma_f32_16x16x32_bf16 v[136:139], v[116:119], v[180:183], v[136:139]
	v_mfma_f32_16x16x32_bf16 v[120:123], v[64:67], v[188:191], v[120:123]
	v_mfma_f32_16x16x32_bf16 v[112:115], v[116:119], v[188:191], v[112:115]
	v_mfma_f32_16x16x32_bf16 v[96:99], v[64:67], v[196:199], v[96:99]
	v_mfma_f32_16x16x32_bf16 v[92:95], v[116:119], v[196:199], v[92:95]
	v_mfma_f32_16x16x32_bf16 v[80:83], v[64:67], v[204:207], v[80:83]
	v_mfma_f32_16x16x32_bf16 v[76:79], v[116:119], v[204:207], v[76:79]
	v_mfma_f32_16x16x32_bf16 v[140:143], v[108:111], v[184:187], v[140:143]
	v_mfma_f32_16x16x32_bf16 v[136:139], v[128:131], v[184:187], v[136:139]
	v_mfma_f32_16x16x32_bf16 v[120:123], v[108:111], v[192:195], v[120:123]
	v_mfma_f32_16x16x32_bf16 v[112:115], v[128:131], v[192:195], v[112:115]
	v_mfma_f32_16x16x32_bf16 v[96:99], v[108:111], v[200:203], v[96:99]
	v_mfma_f32_16x16x32_bf16 v[92:95], v[128:131], v[200:203], v[92:95]
	v_mfma_f32_16x16x32_bf16 v[80:83], v[108:111], v[208:211], v[80:83]
	v_mfma_f32_16x16x32_bf16 v[76:79], v[128:131], v[208:211], v[76:79]
	s_setprio 0
	s_setprio 1
	v_mfma_f32_16x16x32_bf16 v[132:135], v[156:159], v[180:183], v[132:135]
	v_mfma_f32_16x16x32_bf16 v[124:127], v[172:175], v[180:183], v[124:127]
	v_mfma_f32_16x16x32_bf16 v[104:107], v[156:159], v[188:191], v[104:107]
	v_mfma_f32_16x16x32_bf16 v[100:103], v[172:175], v[188:191], v[100:103]
	v_mfma_f32_16x16x32_bf16 v[88:91], v[156:159], v[196:199], v[88:91]
	v_mfma_f32_16x16x32_bf16 v[84:87], v[172:175], v[196:199], v[84:87]
	v_mfma_f32_16x16x32_bf16 v[72:75], v[156:159], v[204:207], v[72:75]
	v_mfma_f32_16x16x32_bf16 v[68:71], v[172:175], v[204:207], v[68:71]
	v_mfma_f32_16x16x32_bf16 v[132:135], v[168:171], v[184:187], v[132:135]
	v_mfma_f32_16x16x32_bf16 v[124:127], v[176:179], v[184:187], v[124:127]
	v_mfma_f32_16x16x32_bf16 v[104:107], v[168:171], v[192:195], v[104:107]
	v_mfma_f32_16x16x32_bf16 v[100:103], v[176:179], v[192:195], v[100:103]
	v_mfma_f32_16x16x32_bf16 v[88:91], v[168:171], v[200:203], v[88:91]
	v_mfma_f32_16x16x32_bf16 v[84:87], v[176:179], v[200:203], v[84:87]
	v_mfma_f32_16x16x32_bf16 v[72:75], v[168:171], v[208:211], v[72:75]
	v_mfma_f32_16x16x32_bf16 v[68:71], v[176:179], v[208:211], v[68:71]
	s_setprio 0
	s_barrier
	s_add_i32 s26, s66, s68
	s_mov_b32 m0, s26
	ds_read_b128 v[180:183], v167 offset:49152
	ds_read_b128 v[184:187], v167 offset:50176
	ds_read_b128 v[188:191], v167 offset:51200
	ds_read_b128 v[192:195], v167 offset:52224
	ds_read_b128 v[196:199], v167 offset:53248
	ds_read_b128 v[200:203], v167 offset:54272
	ds_read_b128 v[204:207], v167 offset:55296
	ds_read_b128 v[208:211], v167 offset:56320
	global_load_lds_dwordx4 v144, s[98:99]
	s_add_i32 m0, s26, 0x2000
	s_add_u32 s26, s30, 0xb0080
	s_addc_u32 s27, s31, 0
	s_add_i32 s30, s67, s68
	global_load_lds_dwordx4 v146, s[98:99]
	s_mov_b32 m0, s30
	s_nop 0
	global_load_lds_dwordx4 v144, s[26:27]
	s_add_i32 m0, s30, 0x2000
	s_nop 0
	global_load_lds_dwordx4 v146, s[26:27]
	s_mov_b32 m0, s47
	s_nop 0
	global_load_lds_dwordx4 v144, s[100:101]
	s_mov_b32 m0, s48
	s_nop 0
	global_load_lds_dwordx4 v146, s[100:101]
	s_waitcnt vmcnt(8)
	s_waitcnt lgkmcnt(0)
	s_barrier
	s_setprio 1
	s_waitcnt lgkmcnt(0)
	v_mfma_f32_16x16x32_bf16 v[60:63], v[64:67], v[180:183], v[60:63]
	v_mfma_f32_16x16x32_bf16 v[56:59], v[116:119], v[180:183], v[56:59]
	v_mfma_f32_16x16x32_bf16 v[44:47], v[64:67], v[188:191], v[44:47]
	v_mfma_f32_16x16x32_bf16 v[40:43], v[116:119], v[188:191], v[40:43]
	v_mfma_f32_16x16x32_bf16 v[28:31], v[64:67], v[196:199], v[28:31]
	v_mfma_f32_16x16x32_bf16 v[24:27], v[116:119], v[196:199], v[24:27]
	v_mfma_f32_16x16x32_bf16 v[12:15], v[64:67], v[204:207], v[12:15]
	v_mfma_f32_16x16x32_bf16 v[8:11], v[116:119], v[204:207], v[8:11]
	v_mfma_f32_16x16x32_bf16 v[60:63], v[108:111], v[184:187], v[60:63]
	v_mfma_f32_16x16x32_bf16 v[56:59], v[128:131], v[184:187], v[56:59]
	v_mfma_f32_16x16x32_bf16 v[44:47], v[108:111], v[192:195], v[44:47]
	v_mfma_f32_16x16x32_bf16 v[40:43], v[128:131], v[192:195], v[40:43]
	v_mfma_f32_16x16x32_bf16 v[28:31], v[108:111], v[200:203], v[28:31]
	v_mfma_f32_16x16x32_bf16 v[24:27], v[128:131], v[200:203], v[24:27]
	v_mfma_f32_16x16x32_bf16 v[12:15], v[108:111], v[208:211], v[12:15]
	v_mfma_f32_16x16x32_bf16 v[8:11], v[128:131], v[208:211], v[8:11]
	s_setprio 0
	s_setprio 1
	v_mfma_f32_16x16x32_bf16 v[52:55], v[156:159], v[180:183], v[52:55]
	v_mfma_f32_16x16x32_bf16 v[48:51], v[172:175], v[180:183], v[48:51]
	v_mfma_f32_16x16x32_bf16 v[36:39], v[156:159], v[188:191], v[36:39]
	v_mfma_f32_16x16x32_bf16 v[32:35], v[172:175], v[188:191], v[32:35]
	v_mfma_f32_16x16x32_bf16 v[20:23], v[156:159], v[196:199], v[20:23]
	v_mfma_f32_16x16x32_bf16 v[16:19], v[172:175], v[196:199], v[16:19]
	v_mfma_f32_16x16x32_bf16 v[4:7], v[156:159], v[204:207], v[4:7]
	v_mfma_f32_16x16x32_bf16 v[0:3], v[172:175], v[204:207], v[0:3]
	v_mfma_f32_16x16x32_bf16 v[52:55], v[168:171], v[184:187], v[52:55]
	v_mfma_f32_16x16x32_bf16 v[48:51], v[176:179], v[184:187], v[48:51]
	v_mfma_f32_16x16x32_bf16 v[36:39], v[168:171], v[192:195], v[36:39]
	v_mfma_f32_16x16x32_bf16 v[32:35], v[176:179], v[192:195], v[32:35]
	v_mfma_f32_16x16x32_bf16 v[20:23], v[168:171], v[200:203], v[20:23]
	v_mfma_f32_16x16x32_bf16 v[16:19], v[176:179], v[200:203], v[16:19]
	v_mfma_f32_16x16x32_bf16 v[4:7], v[168:171], v[208:211], v[4:7]
	v_mfma_f32_16x16x32_bf16 v[0:3], v[176:179], v[208:211], v[0:3]
	s_setprio 0
	s_barrier
	s_add_i32 s65, s65, 2
	s_add_u32 s63, s63, 0x100
	s_addc_u32 s64, s64, 0
	s_cmp_gt_u32 s65, 41
	s_mov_b64 s[26:27], s[28:29]
	s_cbranch_scc0 .LBB0_815
	s_and_b64 vcc, exec, s[10:11]
	s_cbranch_vccz .LBB0_818
	s_barrier
